# conv mixer items with all loads up front; grid barrier polls the arrival counter directly; phase header kernarg loads issued together
# speedup vs baseline: 1.1467x; 1.0186x over previous
_Z11mega_kernel6Paramsii:
	s_mov_b32 s101, 0
	s_load_dword s21, s[0:1], 0x138
	v_writelane_b32 v253, s2, 0
	s_add_u32 s2, s0, 0x138
	s_addc_u32 s3, s1, 0
	v_writelane_b32 v253, s2, 1
	v_and_b32_e32 v1, 0x3ff, v0
	s_nop 0
	v_writelane_b32 v253, s3, 2
	s_mov_b32 s2, 0
	s_ashr_i32 s3, s2, 31
	s_add_u32 s2, s0, s2
	v_writelane_b32 v253, s0, 3
	s_addc_u32 s3, s1, s3
	s_nop 0
	v_writelane_b32 v253, s1, 4
	s_load_dwordx2 s[0:1], s[2:3], 0xb8
	v_cmp_eq_u32_e64 s[2:3], 0, v1
	s_waitcnt lgkmcnt(0)
	v_writelane_b32 v253, s0, 5
	s_nop 1
	v_writelane_b32 v253, s1, 6
	s_getreg_b32 s0, hwreg(HW_REG_XCC_ID, 0, 4)
	s_and_b32 s4, s0, 15
	s_mov_b64 s[0:1], exec
	v_writelane_b32 v253, s2, 7
	s_nop 1
	v_writelane_b32 v253, s3, 8
	s_and_b64 s[2:3], s[0:1], s[2:3]
	s_mov_b64 exec, s[2:3]
	s_cbranch_execz .LBB0_3
	s_add_i32 s5, 0, 0x24000
	s_cmp_lg_u32 s5, -1
	s_mov_b64 s[6:7], src_shared_base
	s_cselect_b32 s5, s5, 0
	s_cselect_b32 s6, s7, 0
	v_mov_b32_e32 v2, s5
	s_add_i32 s5, 0, 0x24004
	s_cmp_lg_u32 s5, -1
	v_mov_b32_e32 v3, s6
	v_mov_b32_e32 v4, 0
	s_cselect_b32 s5, s5, 0
	s_cselect_b32 s6, s7, 0
	s_mov_b64 s[2:3], exec
	flat_store_dword v[2:3], v4 sc0 sc1
	s_waitcnt vmcnt(0)
	v_mov_b32_e32 v2, s5
	v_mov_b32_e32 v3, s6
	flat_store_dword v[2:3], v4 sc0 sc1
	s_waitcnt vmcnt(0)
	v_mbcnt_lo_u32_b32 v2, s2, 0
	v_mbcnt_hi_u32_b32 v2, s3, v2
	v_cmp_eq_u32_e32 vcc, 0, v2
	s_and_b64 s[6:7], exec, vcc
	s_mov_b64 exec, s[6:7]
	s_cbranch_execz .LBB0_3
	s_bcnt1_i32_b64 s2, s[2:3]
	s_lshl_b32 s5, s4, 8
	v_mov_b32_e32 v3, s2
	v_readlane_b32 s2, v253, 5
	v_mov_b32_e32 v2, s5
	v_readlane_b32 s3, v253, 6
	s_nop 4
	global_atomic_add v2, v3, s[2:3] offset:1024

.LBB0_8:
	v_writelane_b32 v254, s78, 24
	s_mov_b32 s0, s49
	s_ashr_i32 s1, s0, 31
	v_writelane_b32 v254, s79, 25
	v_writelane_b32 v254, s76, 26
	v_readlane_b32 s2, v253, 3
	v_readlane_b32 s3, v253, 4
	v_writelane_b32 v254, s77, 27
	v_writelane_b32 v254, s74, 28
	s_add_u32 s0, s2, s0
	s_addc_u32 s1, s3, s1
	v_writelane_b32 v254, s75, 29
	v_writelane_b32 v254, s66, 30
	v_readlane_b32 s24, v253, 62
	v_writelane_b32 v254, s67, 31
	v_readlane_b32 s25, v253, 63
	s_load_dwordx16 s[52:67], s[0:1], 0x0
	s_load_dwordx2 s[30:31], s[0:1], 0x70
	s_load_dwordx4 s[36:39], s[0:1], 0x60
	s_load_dwordx8 s[12:19], s[0:1], 0x40
	s_load_dwordx2 s[2:3], s[0:1], 0x88
	s_load_dwordx8 s[68:75], s[0:1], 0x98
	s_load_dwordx16 s[80:95], s[0:1], 0xc0
	s_load_dwordx4 s[96:99], s[0:1], 0x120
	s_load_dwordx8 s[4:11], s[0:1], 0x100
	s_waitcnt lgkmcnt(0)
	v_writelane_b32 v254, s36, 32
	s_nop 1
	v_writelane_b32 v254, s37, 33
	v_writelane_b32 v254, s38, 34
	v_writelane_b32 v254, s39, 35
	v_writelane_b32 v254, s12, 36
	v_writelane_b32 v254, s13, 37
	v_writelane_b32 v254, s14, 38
	v_writelane_b32 v254, s15, 39
	v_writelane_b32 v254, s16, 40
	v_writelane_b32 v254, s17, 41
	v_writelane_b32 v254, s18, 42
	v_writelane_b32 v254, s19, 43
	v_writelane_b32 v254, s80, 44
	v_writelane_b32 v254, s81, 45
	v_writelane_b32 v254, s82, 46
	v_writelane_b32 v254, s83, 47
	v_writelane_b32 v254, s84, 48
	v_writelane_b32 v254, s85, 49
	v_writelane_b32 v254, s86, 50
	v_writelane_b32 v254, s87, 51
	v_writelane_b32 v254, s88, 52
	v_writelane_b32 v254, s89, 53
	v_writelane_b32 v254, s90, 54
	v_writelane_b32 v254, s91, 55
	v_writelane_b32 v254, s92, 56
	v_writelane_b32 v254, s93, 57
	v_writelane_b32 v254, s94, 58
	v_writelane_b32 v254, s95, 59
	s_mov_b64 s[38:39], s[2:3]
	s_mov_b64 s[36:37], 0x800
	s_mov_b64 s[2:3], 0
	s_mov_b32 s14, s90
	s_mov_b32 s15, s91
	s_mov_b32 s16, s92
	s_mov_b32 s17, s93
	s_mov_b64 s[12:13], -1
	s_mov_b64 s[0:1], 0
	s_mov_b32 s18, 0x800000
	s_movk_i32 s19, 0x1fff
	s_cmp_lt_i32 s46, 19
	s_cbranch_scc1 .LBB0_15
	s_cmp_eq_u32 s46, 19
	s_mov_b64 s[0:1], -1
	s_cbranch_scc0 .LBB0_14
	v_readlane_b32 s0, v253, 0
	v_mov_b32_e32 v2, v1
	s_lshl_b32 s12, s0, 3
	v_ashrrev_i32_e32 v2, 6, v2
	v_add_u32_e32 v6, s12, v2
	s_movk_i32 s0, 0x2000
	v_cmp_gt_i32_e32 vcc, s0, v6
	s_and_saveexec_b64 s[0:1], vcc
	v_readlane_b32 s16, v254, 6
	v_readlane_b32 s17, v254, 7
	s_cbranch_execz .LBB0_13
	v_ashrrev_i32_e32 v3, 31, v2
	s_ashr_i32 s13, s12, 31
	v_lshl_add_u64 v[4:5], v[2:3], 0, s[12:13]
	v_lshlrev_b64 v[2:3], 11, v[4:5]
	v_lshlrev_b64 v[4:5], 12, v[4:5]
	v_lshl_add_u64 v[4:5], s[70:71], 0, v[4:5]
	v_lshl_add_u64 v[2:3], s[74:75], 0, v[2:3]
	v_lshl_add_u64 v[4:5], v[4:5], 0, s[36:37]
	s_mov_b64 s[12:13], 0

.Lbr_exit:
	v_mov_b32_e32 v163, 0
	v_mov_b32_e32 v164, 0x358637bd
	v_mov_b32_e32 v165, 1
	v_mov_b32_e32 v168, 0x2bf
	v_mov_b32_e32 v169, 0
	v_mov_b32_e32 v170, 0x340
	v_mov_b32_e32 v171, 0
	v_mov_b32_e32 v172, 0x33f
	v_mov_b32_e32 v173, 0
	v_mov_b32_e32 v202, 0xc00
	v_mov_b32_e32 v203, 0x7ffffc00
	v_mov_b32_e32 v204, 0xffffff00
	v_mov_b32_e32 v205, 0x400
	v_mov_b32_e32 v206, 0x100
	v_mov_b32_e32 v207, 0x3ff
	v_mov_b32_e32 v208, 0xff
	v_mov_b32_e32 v209, 0xcf
	v_mov_b32_e32 v210, 0xdf
	v_mov_b32_e32 v211, 0xef
	v_mbcnt_lo_u32_b32 v194, -1, 0
	v_mbcnt_hi_u32_b32 v194, -1, v194
	v_and_b32_e32 v195, 64, v194
	v_add_u32_e32 v195, 64, v195
	v_xor_b32_e32 v196, 32, v194
	v_xor_b32_e32 v197, 16, v194
	v_xor_b32_e32 v198, 8, v194
	v_xor_b32_e32 v199, 4, v194
	v_xor_b32_e32 v200, 2, v194
	v_xor_b32_e32 v201, 1, v194
	s_branch .LBB0_309
.Ltr_LBB0_783:
	s_branch .LBB0_783
.Ltr_LBB0_782:
	s_branch .LBB0_782
.Ltr_LBB0_5:
	s_branch .LBB0_5
.LBB0_230:
	v_readlane_b32 s36, v254, 30
	s_mov_b64 s[2:3], 0
	s_mov_b64 s[88:89], -1
	v_readlane_b32 s37, v254, 31
	s_branch .LBB0_311

.LBB0_360:
	v_readlane_b32 s0, v253, 0
	s_barrier
	s_cmpk_gt_i32 s0, 0x7ff
	s_cbranch_scc1 .LBB0_403
	v_readlane_b32 s8, v254, 36
	v_readlane_b32 s9, v254, 37
	v_readlane_b32 s12, v254, 40
	v_readlane_b32 s13, v254, 41
	s_mul_i32 s2, s82, 0x1800
	s_mov_b64 s[8:9], s[12:13]
	s_mul_hi_i32 s1, s82, 0x1800
	s_add_u32 s2, s8, s2
	s_addc_u32 s3, s9, s1
	s_lshl_b32 s1, s0, 3
	s_addk_i32 s1, 0xe000
	v_readlane_b32 s10, v254, 38
	v_readlane_b32 s11, v254, 39
	v_readlane_b32 s14, v254, 42
	v_readlane_b32 s15, v254, 43
	v_lshrrev_b32_e32 v244, 6, v1
	s_nop 0
	v_readfirstlane_b32 s6, v244
	v_and_b32_e32 v244, 63, v1
	v_lshlrev_b32_e32 v245, 5, v244
	v_lshlrev_b32_e32 v244, 4, v244
	v_add_u32_e32 v246, 0x1000, v245
	global_load_dwordx4 v[174:177], v245, s[2:3]
	global_load_dwordx4 v[178:181], v245, s[2:3] offset:16
	global_load_dwordx4 v[182:185], v245, s[2:3] offset:2048
	global_load_dwordx4 v[186:189], v245, s[2:3] offset:2064
	global_load_dwordx4 v[190:193], v246, s[2:3]
	global_load_dwordx4 v[240:243], v246, s[2:3] offset:16
	s_mov_b32 s8, s0
.Lcv_last:
	s_add_u32 s9, s8, s21
	s_cmpk_gt_u32 s9, 0x3ff
	s_cbranch_scc1 .Lcv_lastdone
	s_mov_b32 s8, s9
	s_branch .Lcv_last
.Lcv_lastdone:
	s_mov_b32 s38, 0
	s_mul_i32 s7, s21, 0
	s_add_u32 s7, s7, s0
	s_min_u32 s7, s7, s8
	s_lshl_b32 s12, s7, 3
	s_add_u32 s12, s12, s6
	s_cmpk_lt_u32 s12, 0x1000
	s_movk_i32 s9, 0x3ff
	s_cselect_b32 s9, 0xff, s9
	s_and_b32 s10, s12, s9
	s_mul_i32 s11, s12, 0x3400
	s_cmp_eq_u32 s10, 0
	s_cselect_b32 s39, 0, 0x3400
	s_cselect_b32 s7, 1, 0
	s_or_b32 s38, s38, s7
	s_sub_u32 s39, s11, s39
	s_cmp_eq_u32 s10, s9
	s_cselect_b32 s10, 0, 0x3400
	s_cselect_b32 s7, 2, 0
	s_or_b32 s38, s38, s7
	s_add_u32 s10, s11, s10
	v_add_u32_e32 v247, s11, v244
	global_load_dwordx4 v[72:75], v247, s[4:5]
	global_load_dwordx4 v[76:79], v247, s[4:5] offset:1024
	global_load_dwordx4 v[80:83], v247, s[4:5] offset:2048
	v_add_u32_e32 v247, s39, v244
	global_load_dwordx4 v[84:87], v247, s[4:5] offset:1024
	global_load_dwordx4 v[88:91], v247, s[4:5] offset:2048
	v_add_u32_e32 v247, s10, v244
	global_load_dwordx4 v[92:95], v247, s[4:5] offset:1024
	global_load_dwordx4 v[96:99], v247, s[4:5] offset:2048
	s_mul_i32 s7, s21, 1
	s_add_u32 s7, s7, s0
	s_min_u32 s7, s7, s8
	s_lshl_b32 s13, s7, 3
	s_add_u32 s13, s13, s6
	s_cmpk_lt_u32 s13, 0x1000
	s_movk_i32 s9, 0x3ff
	s_cselect_b32 s9, 0xff, s9
	s_and_b32 s10, s13, s9
	s_mul_i32 s11, s13, 0x3400
	s_cmp_eq_u32 s10, 0
	s_cselect_b32 s39, 0, 0x3400
	s_cselect_b32 s7, 4, 0
	s_or_b32 s38, s38, s7
	s_sub_u32 s39, s11, s39
	s_cmp_eq_u32 s10, s9
	s_cselect_b32 s10, 0, 0x3400
	s_cselect_b32 s7, 8, 0
	s_or_b32 s38, s38, s7
	s_add_u32 s10, s11, s10
	v_add_u32_e32 v247, s11, v244
	global_load_dwordx4 v[100:103], v247, s[4:5]
	global_load_dwordx4 v[104:107], v247, s[4:5] offset:1024
	global_load_dwordx4 v[108:111], v247, s[4:5] offset:2048
	v_add_u32_e32 v247, s39, v244
	global_load_dwordx4 v[112:115], v247, s[4:5] offset:1024
	global_load_dwordx4 v[116:119], v247, s[4:5] offset:2048
	v_add_u32_e32 v247, s10, v244
	global_load_dwordx4 v[120:123], v247, s[4:5] offset:1024
	global_load_dwordx4 v[124:127], v247, s[4:5] offset:2048
	s_mul_i32 s7, s21, 2
	s_add_u32 s7, s7, s0
	s_min_u32 s7, s7, s8
	s_lshl_b32 s14, s7, 3
	s_add_u32 s14, s14, s6
	s_cmpk_lt_u32 s14, 0x1000
	s_movk_i32 s9, 0x3ff
	s_cselect_b32 s9, 0xff, s9
	s_and_b32 s10, s14, s9
	s_mul_i32 s11, s14, 0x3400
	s_cmp_eq_u32 s10, 0
	s_cselect_b32 s39, 0, 0x3400
	s_cselect_b32 s7, 16, 0
	s_or_b32 s38, s38, s7
	s_sub_u32 s39, s11, s39
	s_cmp_eq_u32 s10, s9
	s_cselect_b32 s10, 0, 0x3400
	s_cselect_b32 s7, 32, 0
	s_or_b32 s38, s38, s7
	s_add_u32 s10, s11, s10
	v_add_u32_e32 v247, s11, v244
	global_load_dwordx4 v[128:131], v247, s[4:5]
	global_load_dwordx4 v[132:135], v247, s[4:5] offset:1024
	global_load_dwordx4 v[136:139], v247, s[4:5] offset:2048
	v_add_u32_e32 v247, s39, v244
	global_load_dwordx4 v[140:143], v247, s[4:5] offset:1024
	global_load_dwordx4 v[144:147], v247, s[4:5] offset:2048
	v_add_u32_e32 v247, s10, v244
	global_load_dwordx4 v[148:151], v247, s[4:5] offset:1024
	global_load_dwordx4 v[152:155], v247, s[4:5] offset:2048
	s_mul_i32 s7, s21, 3
	s_add_u32 s7, s7, s0
	s_min_u32 s7, s7, s8
	s_lshl_b32 s15, s7, 3
	s_add_u32 s15, s15, s6
	s_cmpk_lt_u32 s15, 0x1000
	s_movk_i32 s9, 0x3ff
	s_cselect_b32 s9, 0xff, s9
	s_and_b32 s10, s15, s9
	s_mul_i32 s11, s15, 0x3400
	s_cmp_eq_u32 s10, 0
	s_cselect_b32 s39, 0, 0x3400
	s_cselect_b32 s7, 64, 0
	s_or_b32 s38, s38, s7
	s_sub_u32 s39, s11, s39
	s_cmp_eq_u32 s10, s9
	s_cselect_b32 s10, 0, 0x3400
	s_cselect_b32 s7, 128, 0
	s_or_b32 s38, s38, s7
	s_add_u32 s10, s11, s10
	v_add_u32_e32 v247, s11, v244
	global_load_dwordx4 v[212:215], v247, s[4:5]
	global_load_dwordx4 v[216:219], v247, s[4:5] offset:1024
	global_load_dwordx4 v[220:223], v247, s[4:5] offset:2048
	v_add_u32_e32 v247, s39, v244
	global_load_dwordx4 v[224:227], v247, s[4:5] offset:1024
	global_load_dwordx4 v[228:231], v247, s[4:5] offset:2048
	v_add_u32_e32 v247, s10, v244
	global_load_dwordx4 v[232:235], v247, s[4:5] offset:1024
	global_load_dwordx4 v[236:239], v247, s[4:5] offset:2048
	s_waitcnt vmcnt(28)
	s_waitcnt vmcnt(21)
	v_lshlrev_b32_e32 v10, 16, v76
	v_and_b32_e32 v11, 0xffff0000, v76
	v_lshlrev_b32_e32 v12, 16, v80
	v_and_b32_e32 v13, 0xffff0000, v80
	v_pk_mul_f32 v[14:15], v[10:11], v[12:13]
	s_nop 0
	v_pk_mul_f32 v[2:3], v[182:183], v[14:15]
	v_lshlrev_b32_e32 v10, 16, v77
	v_and_b32_e32 v11, 0xffff0000, v77
	v_lshlrev_b32_e32 v12, 16, v81
	v_and_b32_e32 v13, 0xffff0000, v81
	v_pk_mul_f32 v[14:15], v[10:11], v[12:13]
	s_nop 0
	v_pk_mul_f32 v[4:5], v[184:185], v[14:15]
	v_lshlrev_b32_e32 v10, 16, v78
	v_and_b32_e32 v11, 0xffff0000, v78
	v_lshlrev_b32_e32 v12, 16, v82
	v_and_b32_e32 v13, 0xffff0000, v82
	v_pk_mul_f32 v[14:15], v[10:11], v[12:13]
	s_nop 0
	v_pk_mul_f32 v[6:7], v[186:187], v[14:15]
	v_lshlrev_b32_e32 v10, 16, v79
	v_and_b32_e32 v11, 0xffff0000, v79
	v_lshlrev_b32_e32 v12, 16, v83
	v_and_b32_e32 v13, 0xffff0000, v83
	v_pk_mul_f32 v[14:15], v[10:11], v[12:13]
	s_nop 0
	v_pk_mul_f32 v[8:9], v[188:189], v[14:15]
	s_bitcmp1_b32 s38, 0
	s_cbranch_scc1 .Lcv_np0
	v_lshlrev_b32_e32 v10, 16, v84
	v_and_b32_e32 v11, 0xffff0000, v84
	v_lshlrev_b32_e32 v12, 16, v88
	v_and_b32_e32 v13, 0xffff0000, v88
	v_pk_mul_f32 v[14:15], v[10:11], v[12:13]
	s_nop 0
	v_pk_fma_f32 v[2:3], v[174:175], v[14:15], v[2:3]
	v_lshlrev_b32_e32 v10, 16, v85
	v_and_b32_e32 v11, 0xffff0000, v85
	v_lshlrev_b32_e32 v12, 16, v89
	v_and_b32_e32 v13, 0xffff0000, v89
	v_pk_mul_f32 v[14:15], v[10:11], v[12:13]
	s_nop 0
	v_pk_fma_f32 v[4:5], v[176:177], v[14:15], v[4:5]
	v_lshlrev_b32_e32 v10, 16, v86
	v_and_b32_e32 v11, 0xffff0000, v86
	v_lshlrev_b32_e32 v12, 16, v90
	v_and_b32_e32 v13, 0xffff0000, v90
	v_pk_mul_f32 v[14:15], v[10:11], v[12:13]
	s_nop 0
	v_pk_fma_f32 v[6:7], v[178:179], v[14:15], v[6:7]
	v_lshlrev_b32_e32 v10, 16, v87
	v_and_b32_e32 v11, 0xffff0000, v87
	v_lshlrev_b32_e32 v12, 16, v91
	v_and_b32_e32 v13, 0xffff0000, v91
	v_pk_mul_f32 v[14:15], v[10:11], v[12:13]
	s_nop 0
	v_pk_fma_f32 v[8:9], v[180:181], v[14:15], v[8:9]
.Lcv_np0:
	s_bitcmp1_b32 s38, 1
	s_cbranch_scc1 .Lcv_nn0
	v_lshlrev_b32_e32 v10, 16, v92
	v_and_b32_e32 v11, 0xffff0000, v92
	v_lshlrev_b32_e32 v12, 16, v96
	v_and_b32_e32 v13, 0xffff0000, v96
	v_pk_mul_f32 v[14:15], v[10:11], v[12:13]
	s_nop 0
	v_pk_fma_f32 v[2:3], v[190:191], v[14:15], v[2:3]
	v_lshlrev_b32_e32 v10, 16, v93
	v_and_b32_e32 v11, 0xffff0000, v93
	v_lshlrev_b32_e32 v12, 16, v97
	v_and_b32_e32 v13, 0xffff0000, v97
	v_pk_mul_f32 v[14:15], v[10:11], v[12:13]
	s_nop 0
	v_pk_fma_f32 v[4:5], v[192:193], v[14:15], v[4:5]
	v_lshlrev_b32_e32 v10, 16, v94
	v_and_b32_e32 v11, 0xffff0000, v94
	v_lshlrev_b32_e32 v12, 16, v98
	v_and_b32_e32 v13, 0xffff0000, v98
	v_pk_mul_f32 v[14:15], v[10:11], v[12:13]
	s_nop 0
	v_pk_fma_f32 v[6:7], v[240:241], v[14:15], v[6:7]
	v_lshlrev_b32_e32 v10, 16, v95
	v_and_b32_e32 v11, 0xffff0000, v95
	v_lshlrev_b32_e32 v12, 16, v99
	v_and_b32_e32 v13, 0xffff0000, v99
	v_pk_mul_f32 v[14:15], v[10:11], v[12:13]
	s_nop 0
	v_pk_fma_f32 v[8:9], v[242:243], v[14:15], v[8:9]
.Lcv_nn0:
	v_lshlrev_b32_e32 v10, 16, v72
	v_and_b32_e32 v11, 0xffff0000, v72
	v_pk_mul_f32 v[2:3], v[2:3], v[10:11]
	v_lshlrev_b32_e32 v10, 16, v73
	v_and_b32_e32 v11, 0xffff0000, v73
	v_pk_mul_f32 v[4:5], v[4:5], v[10:11]
	v_lshlrev_b32_e32 v10, 16, v74
	v_and_b32_e32 v11, 0xffff0000, v74
	v_pk_mul_f32 v[6:7], v[6:7], v[10:11]
	v_lshlrev_b32_e32 v10, 16, v75
	v_and_b32_e32 v11, 0xffff0000, v75
	v_pk_mul_f32 v[8:9], v[8:9], v[10:11]
	s_nop 0
	v_cvt_pk_bf16_f32 v72, v2, v3
	v_cvt_pk_bf16_f32 v73, v4, v5
	v_cvt_pk_bf16_f32 v74, v6, v7
	v_cvt_pk_bf16_f32 v75, v8, v9
	s_mul_i32 s7, s12, 0xc00
	v_add_u32_e32 v247, s7, v244
	global_store_dwordx4 v247, v[72:75], s[36:37]
	s_waitcnt vmcnt(15)
	v_lshlrev_b32_e32 v10, 16, v104
	v_and_b32_e32 v11, 0xffff0000, v104
	v_lshlrev_b32_e32 v12, 16, v108
	v_and_b32_e32 v13, 0xffff0000, v108
	v_pk_mul_f32 v[14:15], v[10:11], v[12:13]
	s_nop 0
	v_pk_mul_f32 v[2:3], v[182:183], v[14:15]
	v_lshlrev_b32_e32 v10, 16, v105
	v_and_b32_e32 v11, 0xffff0000, v105
	v_lshlrev_b32_e32 v12, 16, v109
	v_and_b32_e32 v13, 0xffff0000, v109
	v_pk_mul_f32 v[14:15], v[10:11], v[12:13]
	s_nop 0
	v_pk_mul_f32 v[4:5], v[184:185], v[14:15]
	v_lshlrev_b32_e32 v10, 16, v106
	v_and_b32_e32 v11, 0xffff0000, v106
	v_lshlrev_b32_e32 v12, 16, v110
	v_and_b32_e32 v13, 0xffff0000, v110
	v_pk_mul_f32 v[14:15], v[10:11], v[12:13]
	s_nop 0
	v_pk_mul_f32 v[6:7], v[186:187], v[14:15]
	v_lshlrev_b32_e32 v10, 16, v107
	v_and_b32_e32 v11, 0xffff0000, v107
	v_lshlrev_b32_e32 v12, 16, v111
	v_and_b32_e32 v13, 0xffff0000, v111
	v_pk_mul_f32 v[14:15], v[10:11], v[12:13]
	s_nop 0
	v_pk_mul_f32 v[8:9], v[188:189], v[14:15]
	s_bitcmp1_b32 s38, 2
	s_cbranch_scc1 .Lcv_np1
	v_lshlrev_b32_e32 v10, 16, v112
	v_and_b32_e32 v11, 0xffff0000, v112
	v_lshlrev_b32_e32 v12, 16, v116
	v_and_b32_e32 v13, 0xffff0000, v116
	v_pk_mul_f32 v[14:15], v[10:11], v[12:13]
	s_nop 0
	v_pk_fma_f32 v[2:3], v[174:175], v[14:15], v[2:3]
	v_lshlrev_b32_e32 v10, 16, v113
	v_and_b32_e32 v11, 0xffff0000, v113
	v_lshlrev_b32_e32 v12, 16, v117
	v_and_b32_e32 v13, 0xffff0000, v117
	v_pk_mul_f32 v[14:15], v[10:11], v[12:13]
	s_nop 0
	v_pk_fma_f32 v[4:5], v[176:177], v[14:15], v[4:5]
	v_lshlrev_b32_e32 v10, 16, v114
	v_and_b32_e32 v11, 0xffff0000, v114
	v_lshlrev_b32_e32 v12, 16, v118
	v_and_b32_e32 v13, 0xffff0000, v118
	v_pk_mul_f32 v[14:15], v[10:11], v[12:13]
	s_nop 0
	v_pk_fma_f32 v[6:7], v[178:179], v[14:15], v[6:7]
	v_lshlrev_b32_e32 v10, 16, v115
	v_and_b32_e32 v11, 0xffff0000, v115
	v_lshlrev_b32_e32 v12, 16, v119
	v_and_b32_e32 v13, 0xffff0000, v119
	v_pk_mul_f32 v[14:15], v[10:11], v[12:13]
	s_nop 0
	v_pk_fma_f32 v[8:9], v[180:181], v[14:15], v[8:9]
.Lcv_np1:
	s_bitcmp1_b32 s38, 3
	s_cbranch_scc1 .Lcv_nn1
	v_lshlrev_b32_e32 v10, 16, v120
	v_and_b32_e32 v11, 0xffff0000, v120
	v_lshlrev_b32_e32 v12, 16, v124
	v_and_b32_e32 v13, 0xffff0000, v124
	v_pk_mul_f32 v[14:15], v[10:11], v[12:13]
	s_nop 0
	v_pk_fma_f32 v[2:3], v[190:191], v[14:15], v[2:3]
	v_lshlrev_b32_e32 v10, 16, v121
	v_and_b32_e32 v11, 0xffff0000, v121
	v_lshlrev_b32_e32 v12, 16, v125
	v_and_b32_e32 v13, 0xffff0000, v125
	v_pk_mul_f32 v[14:15], v[10:11], v[12:13]
	s_nop 0
	v_pk_fma_f32 v[4:5], v[192:193], v[14:15], v[4:5]
	v_lshlrev_b32_e32 v10, 16, v122
	v_and_b32_e32 v11, 0xffff0000, v122
	v_lshlrev_b32_e32 v12, 16, v126
	v_and_b32_e32 v13, 0xffff0000, v126
	v_pk_mul_f32 v[14:15], v[10:11], v[12:13]
	s_nop 0
	v_pk_fma_f32 v[6:7], v[240:241], v[14:15], v[6:7]
	v_lshlrev_b32_e32 v10, 16, v123
	v_and_b32_e32 v11, 0xffff0000, v123
	v_lshlrev_b32_e32 v12, 16, v127
	v_and_b32_e32 v13, 0xffff0000, v127
	v_pk_mul_f32 v[14:15], v[10:11], v[12:13]
	s_nop 0
	v_pk_fma_f32 v[8:9], v[242:243], v[14:15], v[8:9]
.Lcv_nn1:
	v_lshlrev_b32_e32 v10, 16, v100
	v_and_b32_e32 v11, 0xffff0000, v100
	v_pk_mul_f32 v[2:3], v[2:3], v[10:11]
	v_lshlrev_b32_e32 v10, 16, v101
	v_and_b32_e32 v11, 0xffff0000, v101
	v_pk_mul_f32 v[4:5], v[4:5], v[10:11]
	v_lshlrev_b32_e32 v10, 16, v102
	v_and_b32_e32 v11, 0xffff0000, v102
	v_pk_mul_f32 v[6:7], v[6:7], v[10:11]
	v_lshlrev_b32_e32 v10, 16, v103
	v_and_b32_e32 v11, 0xffff0000, v103
	v_pk_mul_f32 v[8:9], v[8:9], v[10:11]
	s_nop 0
	v_cvt_pk_bf16_f32 v100, v2, v3
	v_cvt_pk_bf16_f32 v101, v4, v5
	v_cvt_pk_bf16_f32 v102, v6, v7
	v_cvt_pk_bf16_f32 v103, v8, v9
	s_mul_i32 s7, s13, 0xc00
	v_add_u32_e32 v247, s7, v244
	global_store_dwordx4 v247, v[100:103], s[36:37]
	s_waitcnt vmcnt(9)
	v_lshlrev_b32_e32 v10, 16, v132
	v_and_b32_e32 v11, 0xffff0000, v132
	v_lshlrev_b32_e32 v12, 16, v136
	v_and_b32_e32 v13, 0xffff0000, v136
	v_pk_mul_f32 v[14:15], v[10:11], v[12:13]
	s_nop 0
	v_pk_mul_f32 v[2:3], v[182:183], v[14:15]
	v_lshlrev_b32_e32 v10, 16, v133
	v_and_b32_e32 v11, 0xffff0000, v133
	v_lshlrev_b32_e32 v12, 16, v137
	v_and_b32_e32 v13, 0xffff0000, v137
	v_pk_mul_f32 v[14:15], v[10:11], v[12:13]
	s_nop 0
	v_pk_mul_f32 v[4:5], v[184:185], v[14:15]
	v_lshlrev_b32_e32 v10, 16, v134
	v_and_b32_e32 v11, 0xffff0000, v134
	v_lshlrev_b32_e32 v12, 16, v138
	v_and_b32_e32 v13, 0xffff0000, v138
	v_pk_mul_f32 v[14:15], v[10:11], v[12:13]
	s_nop 0
	v_pk_mul_f32 v[6:7], v[186:187], v[14:15]
	v_lshlrev_b32_e32 v10, 16, v135
	v_and_b32_e32 v11, 0xffff0000, v135
	v_lshlrev_b32_e32 v12, 16, v139
	v_and_b32_e32 v13, 0xffff0000, v139
	v_pk_mul_f32 v[14:15], v[10:11], v[12:13]
	s_nop 0
	v_pk_mul_f32 v[8:9], v[188:189], v[14:15]
	s_bitcmp1_b32 s38, 4
	s_cbranch_scc1 .Lcv_np2
	v_lshlrev_b32_e32 v10, 16, v140
	v_and_b32_e32 v11, 0xffff0000, v140
	v_lshlrev_b32_e32 v12, 16, v144
	v_and_b32_e32 v13, 0xffff0000, v144
	v_pk_mul_f32 v[14:15], v[10:11], v[12:13]
	s_nop 0
	v_pk_fma_f32 v[2:3], v[174:175], v[14:15], v[2:3]
	v_lshlrev_b32_e32 v10, 16, v141
	v_and_b32_e32 v11, 0xffff0000, v141
	v_lshlrev_b32_e32 v12, 16, v145
	v_and_b32_e32 v13, 0xffff0000, v145
	v_pk_mul_f32 v[14:15], v[10:11], v[12:13]
	s_nop 0
	v_pk_fma_f32 v[4:5], v[176:177], v[14:15], v[4:5]
	v_lshlrev_b32_e32 v10, 16, v142
	v_and_b32_e32 v11, 0xffff0000, v142
	v_lshlrev_b32_e32 v12, 16, v146
	v_and_b32_e32 v13, 0xffff0000, v146
	v_pk_mul_f32 v[14:15], v[10:11], v[12:13]
	s_nop 0
	v_pk_fma_f32 v[6:7], v[178:179], v[14:15], v[6:7]
	v_lshlrev_b32_e32 v10, 16, v143
	v_and_b32_e32 v11, 0xffff0000, v143
	v_lshlrev_b32_e32 v12, 16, v147
	v_and_b32_e32 v13, 0xffff0000, v147
	v_pk_mul_f32 v[14:15], v[10:11], v[12:13]
	s_nop 0
	v_pk_fma_f32 v[8:9], v[180:181], v[14:15], v[8:9]
.Lcv_np2:
	s_bitcmp1_b32 s38, 5
	s_cbranch_scc1 .Lcv_nn2
	v_lshlrev_b32_e32 v10, 16, v148
	v_and_b32_e32 v11, 0xffff0000, v148
	v_lshlrev_b32_e32 v12, 16, v152
	v_and_b32_e32 v13, 0xffff0000, v152
	v_pk_mul_f32 v[14:15], v[10:11], v[12:13]
	s_nop 0
	v_pk_fma_f32 v[2:3], v[190:191], v[14:15], v[2:3]
	v_lshlrev_b32_e32 v10, 16, v149
	v_and_b32_e32 v11, 0xffff0000, v149
	v_lshlrev_b32_e32 v12, 16, v153
	v_and_b32_e32 v13, 0xffff0000, v153
	v_pk_mul_f32 v[14:15], v[10:11], v[12:13]
	s_nop 0
	v_pk_fma_f32 v[4:5], v[192:193], v[14:15], v[4:5]
	v_lshlrev_b32_e32 v10, 16, v150
	v_and_b32_e32 v11, 0xffff0000, v150
	v_lshlrev_b32_e32 v12, 16, v154
	v_and_b32_e32 v13, 0xffff0000, v154
	v_pk_mul_f32 v[14:15], v[10:11], v[12:13]
	s_nop 0
	v_pk_fma_f32 v[6:7], v[240:241], v[14:15], v[6:7]
	v_lshlrev_b32_e32 v10, 16, v151
	v_and_b32_e32 v11, 0xffff0000, v151
	v_lshlrev_b32_e32 v12, 16, v155
	v_and_b32_e32 v13, 0xffff0000, v155
	v_pk_mul_f32 v[14:15], v[10:11], v[12:13]
	s_nop 0
	v_pk_fma_f32 v[8:9], v[242:243], v[14:15], v[8:9]
.Lcv_nn2:
	v_lshlrev_b32_e32 v10, 16, v128
	v_and_b32_e32 v11, 0xffff0000, v128
	v_pk_mul_f32 v[2:3], v[2:3], v[10:11]
	v_lshlrev_b32_e32 v10, 16, v129
	v_and_b32_e32 v11, 0xffff0000, v129
	v_pk_mul_f32 v[4:5], v[4:5], v[10:11]
	v_lshlrev_b32_e32 v10, 16, v130
	v_and_b32_e32 v11, 0xffff0000, v130
	v_pk_mul_f32 v[6:7], v[6:7], v[10:11]
	v_lshlrev_b32_e32 v10, 16, v131
	v_and_b32_e32 v11, 0xffff0000, v131
	v_pk_mul_f32 v[8:9], v[8:9], v[10:11]
	s_nop 0
	v_cvt_pk_bf16_f32 v128, v2, v3
	v_cvt_pk_bf16_f32 v129, v4, v5
	v_cvt_pk_bf16_f32 v130, v6, v7
	v_cvt_pk_bf16_f32 v131, v8, v9
	s_mul_i32 s7, s14, 0xc00
	v_add_u32_e32 v247, s7, v244
	global_store_dwordx4 v247, v[128:131], s[36:37]
	s_waitcnt vmcnt(3)
	v_lshlrev_b32_e32 v10, 16, v216
	v_and_b32_e32 v11, 0xffff0000, v216
	v_lshlrev_b32_e32 v12, 16, v220
	v_and_b32_e32 v13, 0xffff0000, v220
	v_pk_mul_f32 v[14:15], v[10:11], v[12:13]
	s_nop 0
	v_pk_mul_f32 v[2:3], v[182:183], v[14:15]
	v_lshlrev_b32_e32 v10, 16, v217
	v_and_b32_e32 v11, 0xffff0000, v217
	v_lshlrev_b32_e32 v12, 16, v221
	v_and_b32_e32 v13, 0xffff0000, v221
	v_pk_mul_f32 v[14:15], v[10:11], v[12:13]
	s_nop 0
	v_pk_mul_f32 v[4:5], v[184:185], v[14:15]
	v_lshlrev_b32_e32 v10, 16, v218
	v_and_b32_e32 v11, 0xffff0000, v218
	v_lshlrev_b32_e32 v12, 16, v222
	v_and_b32_e32 v13, 0xffff0000, v222
	v_pk_mul_f32 v[14:15], v[10:11], v[12:13]
	s_nop 0
	v_pk_mul_f32 v[6:7], v[186:187], v[14:15]
	v_lshlrev_b32_e32 v10, 16, v219
	v_and_b32_e32 v11, 0xffff0000, v219
	v_lshlrev_b32_e32 v12, 16, v223
	v_and_b32_e32 v13, 0xffff0000, v223
	v_pk_mul_f32 v[14:15], v[10:11], v[12:13]
	s_nop 0
	v_pk_mul_f32 v[8:9], v[188:189], v[14:15]
	s_bitcmp1_b32 s38, 6
	s_cbranch_scc1 .Lcv_np3
	v_lshlrev_b32_e32 v10, 16, v224
	v_and_b32_e32 v11, 0xffff0000, v224
	v_lshlrev_b32_e32 v12, 16, v228
	v_and_b32_e32 v13, 0xffff0000, v228
	v_pk_mul_f32 v[14:15], v[10:11], v[12:13]
	s_nop 0
	v_pk_fma_f32 v[2:3], v[174:175], v[14:15], v[2:3]
	v_lshlrev_b32_e32 v10, 16, v225
	v_and_b32_e32 v11, 0xffff0000, v225
	v_lshlrev_b32_e32 v12, 16, v229
	v_and_b32_e32 v13, 0xffff0000, v229
	v_pk_mul_f32 v[14:15], v[10:11], v[12:13]
	s_nop 0
	v_pk_fma_f32 v[4:5], v[176:177], v[14:15], v[4:5]
	v_lshlrev_b32_e32 v10, 16, v226
	v_and_b32_e32 v11, 0xffff0000, v226
	v_lshlrev_b32_e32 v12, 16, v230
	v_and_b32_e32 v13, 0xffff0000, v230
	v_pk_mul_f32 v[14:15], v[10:11], v[12:13]
	s_nop 0
	v_pk_fma_f32 v[6:7], v[178:179], v[14:15], v[6:7]
	v_lshlrev_b32_e32 v10, 16, v227
	v_and_b32_e32 v11, 0xffff0000, v227
	v_lshlrev_b32_e32 v12, 16, v231
	v_and_b32_e32 v13, 0xffff0000, v231
	v_pk_mul_f32 v[14:15], v[10:11], v[12:13]
	s_nop 0
	v_pk_fma_f32 v[8:9], v[180:181], v[14:15], v[8:9]
.Lcv_np3:
	s_bitcmp1_b32 s38, 7
	s_cbranch_scc1 .Lcv_nn3
	v_lshlrev_b32_e32 v10, 16, v232
	v_and_b32_e32 v11, 0xffff0000, v232
	v_lshlrev_b32_e32 v12, 16, v236
	v_and_b32_e32 v13, 0xffff0000, v236
	v_pk_mul_f32 v[14:15], v[10:11], v[12:13]
	s_nop 0
	v_pk_fma_f32 v[2:3], v[190:191], v[14:15], v[2:3]
	v_lshlrev_b32_e32 v10, 16, v233
	v_and_b32_e32 v11, 0xffff0000, v233
	v_lshlrev_b32_e32 v12, 16, v237
	v_and_b32_e32 v13, 0xffff0000, v237
	v_pk_mul_f32 v[14:15], v[10:11], v[12:13]
	s_nop 0
	v_pk_fma_f32 v[4:5], v[192:193], v[14:15], v[4:5]
	v_lshlrev_b32_e32 v10, 16, v234
	v_and_b32_e32 v11, 0xffff0000, v234
	v_lshlrev_b32_e32 v12, 16, v238
	v_and_b32_e32 v13, 0xffff0000, v238
	v_pk_mul_f32 v[14:15], v[10:11], v[12:13]
	s_nop 0
	v_pk_fma_f32 v[6:7], v[240:241], v[14:15], v[6:7]
	v_lshlrev_b32_e32 v10, 16, v235
	v_and_b32_e32 v11, 0xffff0000, v235
	v_lshlrev_b32_e32 v12, 16, v239
	v_and_b32_e32 v13, 0xffff0000, v239
	v_pk_mul_f32 v[14:15], v[10:11], v[12:13]
	s_nop 0
	v_pk_fma_f32 v[8:9], v[242:243], v[14:15], v[8:9]
.Lcv_nn3:
	v_lshlrev_b32_e32 v10, 16, v212
	v_and_b32_e32 v11, 0xffff0000, v212
	v_pk_mul_f32 v[2:3], v[2:3], v[10:11]
	v_lshlrev_b32_e32 v10, 16, v213
	v_and_b32_e32 v11, 0xffff0000, v213
	v_pk_mul_f32 v[4:5], v[4:5], v[10:11]
	v_lshlrev_b32_e32 v10, 16, v214
	v_and_b32_e32 v11, 0xffff0000, v214
	v_pk_mul_f32 v[6:7], v[6:7], v[10:11]
	v_lshlrev_b32_e32 v10, 16, v215
	v_and_b32_e32 v11, 0xffff0000, v215
	v_pk_mul_f32 v[8:9], v[8:9], v[10:11]
	s_nop 0
	v_cvt_pk_bf16_f32 v212, v2, v3
	v_cvt_pk_bf16_f32 v213, v4, v5
	v_cvt_pk_bf16_f32 v214, v6, v7
	v_cvt_pk_bf16_f32 v215, v8, v9
	s_mul_i32 s7, s15, 0xc00
	v_add_u32_e32 v247, s7, v244
	global_store_dwordx4 v247, v[212:215], s[36:37]
.Lcv_adv:
	s_cmpk_gt_i32 s0, 0x3ff
	s_cbranch_scc1 .Lcv_advdone
	s_add_i32 s0, s0, s21
	s_add_i32 s1, s1, s86
	s_branch .Lcv_adv
.Lcv_advdone:
	s_cmpk_gt_i32 s0, 0x7ff
	s_cbranch_scc1 .LBB0_403
	s_branch .LBB0_364

.LBB0_678:
	s_branch .Ln1t_entry
	s_cmp_gt_i32 s10, -1
	s_mov_b64 s[0:1], -1
	s_cbranch_scc0 .LBB0_680
	s_and_b32 s0, s10, 0xffff
	s_mulk_i32 s0, 0x4ec5
	s_lshr_b32 s1, s0, 21
	s_lshr_b32 s0, s0, 14
	s_mulk_i32 s1, 0x68
	s_and_b32 s2, s0, 0xff80
	s_sub_i32 s1, s10, s1
	s_mul_i32 s0, s2, 0x6800
	s_add_u32 s0, s11, s0
	s_addc_u32 s3, s12, 0
	s_lshl_b32 s1, s1, 6
	s_and_b32 s6, s1, 0xffc0
	v_mov_b32_e32 v18, v1
	s_lshl_b32 s1, s6, 2
	s_add_u32 s0, s0, s1
	v_lshlrev_b32_e32 v20, 4, v18
	s_addc_u32 s1, s3, 0
	v_ashrrev_i32_e32 v19, 4, v18
	v_and_b32_e32 v162, 0xf0, v20
	v_lshl_add_u64 v[14:15], s[0:1], 0, v[162:163]
	s_movk_i32 s3, 0x6800
	v_add_u32_e32 v4, 32, v19
	v_mad_i64_i32 v[2:3], s[0:1], v19, s3, v[14:15]
	v_mad_i64_i32 v[6:7], s[0:1], v4, s3, v[14:15]
	global_load_dwordx4 v[2:5], v[2:3], off
	s_nop 0
	global_load_dwordx4 v[6:9], v[6:7], off
	v_add_u32_e32 v10, 64, v19
	v_mad_i64_i32 v[10:11], s[0:1], v10, s3, v[14:15]
	global_load_dwordx4 v[10:13], v[10:11], off
	v_add_u32_e32 v16, 0x60, v19
	v_mad_i64_i32 v[14:15], s[0:1], v16, s3, v[14:15]
	global_load_dwordx4 v[14:17], v[14:15], off
	s_movk_i32 s0, 0x104
	v_mul_lo_u32 v19, v19, s0
	v_and_b32_e32 v20, 0x70, v20
	v_ashrrev_i32_e32 v18, 3, v18
	v_add3_u32 v22, 0, v162, v19
	v_mul_u32_u24_e32 v19, 0x41, v20
	v_lshlrev_b32_e32 v21, 2, v18
	v_lshlrev_b32_e32 v19, 2, v19
	v_add3_u32 v29, 0, v21, v19
	v_add3_u32 v21, 0, v19, v21
	v_add_u32_e32 v18, s6, v18
	v_add_u32_e32 v23, 0x2080, v22
	v_add_u32_e32 v24, 0x2088, v22
	v_add_u32_e32 v25, 0x4100, v22
	v_add_u32_e32 v26, 0x4108, v22
	v_add_u32_e32 v27, 0x6180, v22
	v_add_u32_e32 v28, 0x6188, v22
	v_add_u32_e32 v30, 0x800, v21
	v_add_u32_e32 v31, 0x400, v29
	v_add_u32_e32 v32, 0x400, v21
	v_add_u32_e32 v33, 0xc00, v21
	v_ashrrev_i32_e32 v19, 31, v18
	v_readlane_b32 s68, v254, 44
	v_lshlrev_b64 v[18:19], 11, v[18:19]
	v_readlane_b32 s72, v254, 48
	v_readlane_b32 s73, v254, 49
	s_lshl_b32 s48, s2, 1
	v_lshlrev_b32_e32 v162, 1, v20
	v_lshl_add_u64 v[18:19], s[72:73], 0, v[18:19]
	v_lshl_add_u64 v[18:19], v[18:19], 0, s[48:49]
	v_lshl_add_u64 v[18:19], v[18:19], 0, v[162:163]
	v_readlane_b32 s69, v254, 45
	v_readlane_b32 s70, v254, 46
	v_readlane_b32 s71, v254, 47
	v_readlane_b32 s74, v254, 50
	v_readlane_b32 s75, v254, 51
	v_readlane_b32 s76, v254, 52
	v_readlane_b32 s77, v254, 53
	v_readlane_b32 s78, v254, 54
	v_readlane_b32 s79, v254, 55
	v_readlane_b32 s80, v254, 56
	v_readlane_b32 s81, v254, 57
	v_readlane_b32 s82, v254, 58
	v_readlane_b32 s83, v254, 59
	s_mov_b64 s[0:1], 0
	s_waitcnt vmcnt(3)
	ds_write2_b32 v22, v2, v3 offset1:1
	ds_write2_b32 v22, v4, v5 offset0:2 offset1:3
	s_waitcnt vmcnt(2)
	ds_write2_b32 v23, v6, v7 offset1:1
	ds_write2_b32 v24, v8, v9 offset1:1
	s_waitcnt vmcnt(1)
	ds_write2_b32 v25, v10, v11 offset1:1
	ds_write2_b32 v26, v12, v13 offset1:1
	s_waitcnt vmcnt(0)
	ds_write2_b32 v27, v14, v15 offset1:1
	ds_write2_b32 v28, v16, v17 offset1:1
	s_waitcnt lgkmcnt(0)
	s_barrier
	ds_read2_b32 v[2:3], v29 offset1:130
	ds_read2_b32 v[4:5], v21 offset0:65 offset1:195
	ds_read2_b32 v[6:7], v30 offset0:8 offset1:73
	ds_read2_b32 v[8:9], v30 offset0:138 offset1:203
	ds_read2_b32 v[10:11], v31 offset0:4 offset1:134
	ds_read2_b32 v[12:13], v32 offset0:69 offset1:199
	ds_read2_b32 v[14:15], v33 offset0:12 offset1:77
	ds_read2_b32 v[16:17], v33 offset0:142 offset1:207
	s_waitcnt lgkmcnt(6)
	v_cvt_pk_bf16_f32 v2, v2, v4
	v_cvt_pk_bf16_f32 v3, v3, v5
	s_waitcnt lgkmcnt(2)
	v_cvt_pk_bf16_f32 v4, v10, v12
	v_cvt_pk_bf16_f32 v5, v11, v13
	v_cvt_pk_bf16_f32 v6, v6, v7
	v_cvt_pk_bf16_f32 v7, v8, v9
	s_waitcnt lgkmcnt(1)
	v_cvt_pk_bf16_f32 v8, v14, v15
	s_waitcnt lgkmcnt(0)
	v_cvt_pk_bf16_f32 v9, v16, v17
	global_store_dwordx4 v[18:19], v[2:5], off
	global_store_dwordx4 v[18:19], v[6:9], off offset:16
	s_barrier

.Ln1t_entry:
	v_readlane_b32 s68, v254, 38
	v_readlane_b32 s69, v254, 39
	v_readlane_b32 s70, v254, 48
	v_readlane_b32 s71, v254, 49
	s_nop 3
	s_add_u32 s68, s68, 0x1a00000
	s_addc_u32 s69, s69, 0
	s_mov_b32 s73, s21
	s_mov_b32 s74, s10
	s_cmpk_gt_i32 s74, 0x33f
	s_cbranch_scc1 .LBB0_692
	s_mov_b32 s72, s74
.Ln1t_klast:
	s_add_u32 s0, s72, s73
	s_cmpk_gt_u32 s0, 0x33f
	s_cbranch_scc1 .Ln1t_kdone
	s_mov_b32 s72, s0
	s_branch .Ln1t_klast
.Ln1t_kdone:
	v_lshrrev_b32_e32 v112, 4, v1
	v_and_b32_e32 v113, 15, v1
	v_lshlrev_b32_e32 v113, 4, v113
	v_mul_u32_u24_e32 v114, 0x104, v112
	v_add_u32_e32 v114, v114, v113
	v_lshrrev_b32_e32 v116, 3, v1
	v_and_b32_e32 v117, 7, v1
	v_mul_u32_u24_e32 v115, 0x1040, v117
	v_lshl_add_u32 v115, v116, 2, v115
	v_lshlrev_b32_e32 v117, 5, v117
	s_mul_i32 s48, s73, 0
	s_add_u32 s48, s48, s74
	s_min_u32 s48, s48, s72
	s_mov_b32 s0, s48
	s_mul_i32 s2, s0, 0x4ed
	s_lshr_b32 s2, s2, 17
	s_mul_i32 s3, s2, 0x68
	s_sub_u32 s3, s0, s3
	s_mul_i32 s14, s2, 0x340000
	s_lshl_b32 s0, s3, 8
	s_add_u32 s14, s14, s0
	s_add_u32 s6, s68, s14
	s_addc_u32 s7, s69, 0
	s_lshl_b32 s14, s3, 17
	s_lshl_b32 s0, s2, 8
	s_add_u32 s14, s14, s0
	s_add_u32 s8, s70, s14
	s_addc_u32 s9, s71, 0
	s_movk_i32 s12, 0x6800
	s_movk_i32 s13, 0x800
	v_mul_lo_u32 v123, v112, s12
	v_add_u32_e32 v118, v123, v113
	s_lshl_b32 vcc_lo, s12, 5
	v_add_u32_e32 v119, vcc_lo, v118
	v_add_u32_e32 v120, vcc_lo, v119
	v_add_u32_e32 v121, vcc_lo, v120
	global_load_dwordx4 v[40:43], v118, s[6:7]
	global_load_dwordx4 v[44:47], v119, s[6:7]
	global_load_dwordx4 v[48:51], v120, s[6:7]
	global_load_dwordx4 v[52:55], v121, s[6:7]
	s_mul_i32 s48, s73, 1
	s_add_u32 s48, s48, s74
	s_min_u32 s48, s48, s72
	s_mov_b32 s0, s48
	s_mul_i32 s2, s0, 0x4ed
	s_lshr_b32 s2, s2, 17
	s_mul_i32 s3, s2, 0x68
	s_sub_u32 s3, s0, s3
	s_mul_i32 s14, s2, 0x340000
	s_lshl_b32 s0, s3, 8
	s_add_u32 s14, s14, s0
	s_add_u32 s6, s68, s14
	s_addc_u32 s7, s69, 0
	s_lshl_b32 s14, s3, 17
	s_lshl_b32 s0, s2, 8
	s_add_u32 s14, s14, s0
	s_add_u32 s8, s70, s14
	s_addc_u32 s9, s71, 0
	s_movk_i32 s12, 0x6800
	s_movk_i32 s13, 0x800
	v_mul_lo_u32 v123, v112, s12
	v_add_u32_e32 v118, v123, v113
	s_lshl_b32 vcc_lo, s12, 5
	v_add_u32_e32 v119, vcc_lo, v118
	v_add_u32_e32 v120, vcc_lo, v119
	v_add_u32_e32 v121, vcc_lo, v120
	global_load_dwordx4 v[56:59], v118, s[6:7]
	global_load_dwordx4 v[60:63], v119, s[6:7]
	global_load_dwordx4 v[64:67], v120, s[6:7]
	global_load_dwordx4 v[68:71], v121, s[6:7]
	s_waitcnt vmcnt(4)
	ds_write_b32 v114, v40 offset:0
	ds_write_b32 v114, v41 offset:4
	ds_write_b32 v114, v42 offset:8
	ds_write_b32 v114, v43 offset:12
	ds_write_b32 v114, v44 offset:8320
	ds_write_b32 v114, v45 offset:8324
	ds_write_b32 v114, v46 offset:8328
	ds_write_b32 v114, v47 offset:8332
	ds_write_b32 v114, v48 offset:16640
	ds_write_b32 v114, v49 offset:16644
	ds_write_b32 v114, v50 offset:16648
	ds_write_b32 v114, v51 offset:16652
	ds_write_b32 v114, v52 offset:24960
	ds_write_b32 v114, v53 offset:24964
	ds_write_b32 v114, v54 offset:24968
	ds_write_b32 v114, v55 offset:24972
	s_waitcnt lgkmcnt(0)
	s_barrier
	ds_read_b32 v88, v115 offset:0
	ds_read_b32 v89, v115 offset:260
	ds_read_b32 v90, v115 offset:520
	ds_read_b32 v91, v115 offset:780
	ds_read_b32 v92, v115 offset:1040
	ds_read_b32 v93, v115 offset:1300
	ds_read_b32 v94, v115 offset:1560
	ds_read_b32 v95, v115 offset:1820
	ds_read_b32 v96, v115 offset:2080
	ds_read_b32 v97, v115 offset:2340
	ds_read_b32 v98, v115 offset:2600
	ds_read_b32 v99, v115 offset:2860
	ds_read_b32 v100, v115 offset:3120
	ds_read_b32 v101, v115 offset:3380
	ds_read_b32 v102, v115 offset:3640
	ds_read_b32 v103, v115 offset:3900
	s_mul_i32 s48, s73, 0
	s_add_u32 s48, s48, s74
	s_min_u32 s48, s48, s72
	s_mov_b32 s0, s48
	s_mul_i32 s2, s0, 0x4ed
	s_lshr_b32 s2, s2, 17
	s_mul_i32 s3, s2, 0x68
	s_sub_u32 s3, s0, s3
	s_mul_i32 s14, s2, 0x340000
	s_lshl_b32 s0, s3, 8
	s_add_u32 s14, s14, s0
	s_add_u32 s6, s68, s14
	s_addc_u32 s7, s69, 0
	s_lshl_b32 s14, s3, 17
	s_lshl_b32 s0, s2, 8
	s_add_u32 s14, s14, s0
	s_add_u32 s8, s70, s14
	s_addc_u32 s9, s71, 0
	s_movk_i32 s12, 0x6800
	s_movk_i32 s13, 0x800
	v_mul_lo_u32 v122, v116, s13
	v_add_u32_e32 v122, v122, v117
	s_waitcnt lgkmcnt(0)
	v_cvt_pk_bf16_f32 v104, v88, v89
	v_cvt_pk_bf16_f32 v105, v90, v91
	v_cvt_pk_bf16_f32 v106, v92, v93
	v_cvt_pk_bf16_f32 v107, v94, v95
	v_cvt_pk_bf16_f32 v108, v96, v97
	v_cvt_pk_bf16_f32 v109, v98, v99
	v_cvt_pk_bf16_f32 v110, v100, v101
	v_cvt_pk_bf16_f32 v111, v102, v103
	global_store_dwordx4 v122, v[104:107], s[8:9]
	global_store_dwordx4 v122, v[108:111], s[8:9] offset:16
	s_nop 1
	s_waitcnt vmcnt(2)
	ds_write_b32 v114, v56 offset:33792
	ds_write_b32 v114, v57 offset:33796
	ds_write_b32 v114, v58 offset:33800
	ds_write_b32 v114, v59 offset:33804
	ds_write_b32 v114, v60 offset:42112
	ds_write_b32 v114, v61 offset:42116
	ds_write_b32 v114, v62 offset:42120
	ds_write_b32 v114, v63 offset:42124
	ds_write_b32 v114, v64 offset:50432
	ds_write_b32 v114, v65 offset:50436
	ds_write_b32 v114, v66 offset:50440
	ds_write_b32 v114, v67 offset:50444
	ds_write_b32 v114, v68 offset:58752
	ds_write_b32 v114, v69 offset:58756
	ds_write_b32 v114, v70 offset:58760
	ds_write_b32 v114, v71 offset:58764
	s_waitcnt lgkmcnt(0)
	s_barrier
	ds_read_b32 v88, v115 offset:33792
	ds_read_b32 v89, v115 offset:34052
	ds_read_b32 v90, v115 offset:34312
	ds_read_b32 v91, v115 offset:34572
	ds_read_b32 v92, v115 offset:34832
	ds_read_b32 v93, v115 offset:35092
	ds_read_b32 v94, v115 offset:35352
	ds_read_b32 v95, v115 offset:35612
	ds_read_b32 v96, v115 offset:35872
	ds_read_b32 v97, v115 offset:36132
	ds_read_b32 v98, v115 offset:36392
	ds_read_b32 v99, v115 offset:36652
	ds_read_b32 v100, v115 offset:36912
	ds_read_b32 v101, v115 offset:37172
	ds_read_b32 v102, v115 offset:37432
	ds_read_b32 v103, v115 offset:37692
	s_mul_i32 s48, s73, 1
	s_add_u32 s48, s48, s74
	s_min_u32 s48, s48, s72
	s_mov_b32 s0, s48
	s_mul_i32 s2, s0, 0x4ed
	s_lshr_b32 s2, s2, 17
	s_mul_i32 s3, s2, 0x68
	s_sub_u32 s3, s0, s3
	s_mul_i32 s14, s2, 0x340000
	s_lshl_b32 s0, s3, 8
	s_add_u32 s14, s14, s0
	s_add_u32 s6, s68, s14
	s_addc_u32 s7, s69, 0
	s_lshl_b32 s14, s3, 17
	s_lshl_b32 s0, s2, 8
	s_add_u32 s14, s14, s0
	s_add_u32 s8, s70, s14
	s_addc_u32 s9, s71, 0
	s_movk_i32 s12, 0x6800
	s_movk_i32 s13, 0x800
	v_mul_lo_u32 v122, v116, s13
	v_add_u32_e32 v122, v122, v117
	s_waitcnt lgkmcnt(0)
	v_cvt_pk_bf16_f32 v104, v88, v89
	v_cvt_pk_bf16_f32 v105, v90, v91
	v_cvt_pk_bf16_f32 v106, v92, v93
	v_cvt_pk_bf16_f32 v107, v94, v95
	v_cvt_pk_bf16_f32 v108, v96, v97
	v_cvt_pk_bf16_f32 v109, v98, v99
	v_cvt_pk_bf16_f32 v110, v100, v101
	v_cvt_pk_bf16_f32 v111, v102, v103
	global_store_dwordx4 v122, v[104:107], s[8:9]
	global_store_dwordx4 v122, v[108:111], s[8:9] offset:16
	s_nop 1
	s_waitcnt vmcnt(0)
	s_barrier
	s_branch .LBB0_692

.LBB0_698:
	s_cmpk_gt_i32 s12, 0xdf
	s_cbranch_scc1 .Lp0t_entry
	s_cmpk_gt_i32 s12, 0xbf
	s_cbranch_scc0 .LBB0_701
	s_cmpk_gt_u32 s12, 0xdf
	s_cbranch_scc0 .LBB0_702
	s_add_i32 s6, s12, 0xff20
	s_and_b32 s7, s6, 0xffff
	s_mulk_i32 s7, 0x4ec5
	s_lshr_b32 s8, s7, 21
	s_lshr_b32 s7, s7, 14
	v_readlane_b32 s92, v254, 36
	s_mulk_i32 s8, 0x68
	s_and_b32 s10, s7, 0xff80
	v_readlane_b32 s94, v254, 38
	v_readlane_b32 s95, v254, 39
	s_sub_i32 s6, s6, s8
	s_mul_i32 s7, s10, 0x6800
	s_mov_b64 s[38:39], s[94:95]
	s_add_u32 s7, s38, s7
	s_addc_u32 s8, s39, 0
	s_lshl_b32 s6, s6, 6
	s_and_b32 s11, s6, 0xffc0
	s_waitcnt vmcnt(29)
	v_mov_b32_e32 v18, v1
	s_lshl_b32 s6, s11, 2
	s_add_u32 s6, s7, s6
	v_lshlrev_b32_e32 v20, 4, v18
	s_addc_u32 s7, s8, 0
	v_ashrrev_i32_e32 v19, 4, v18
	v_and_b32_e32 v162, 0xf0, v20
	v_lshl_add_u64 v[14:15], s[6:7], 0, v[162:163]
	s_movk_i32 s8, 0x6800
	v_add_u32_e32 v4, 32, v19
	v_mad_i64_i32 v[2:3], s[6:7], v19, s8, v[14:15]
	v_mad_i64_i32 v[6:7], s[6:7], v4, s8, v[14:15]
	global_load_dwordx4 v[2:5], v[2:3], off
	s_nop 0
	global_load_dwordx4 v[6:9], v[6:7], off
	v_add_u32_e32 v10, 64, v19
	v_mad_i64_i32 v[10:11], s[6:7], v10, s8, v[14:15]
	global_load_dwordx4 v[10:13], v[10:11], off
	v_add_u32_e32 v16, 0x60, v19
	v_mad_i64_i32 v[14:15], s[6:7], v16, s8, v[14:15]
	global_load_dwordx4 v[14:17], v[14:15], off
	s_movk_i32 s6, 0x104
	v_mul_lo_u32 v19, v19, s6
	v_and_b32_e32 v20, 0x70, v20
	v_readlane_b32 s93, v254, 37
	v_readlane_b32 s96, v254, 40
	v_readlane_b32 s97, v254, 41
	v_readlane_b32 s98, v254, 42
	v_readlane_b32 s99, v254, 43
	v_ashrrev_i32_e32 v18, 3, v18
	s_waitcnt vmcnt(32)
	v_add3_u32 v22, 0, v162, v19
	v_mul_u32_u24_e32 v19, 0x41, v20
	v_readlane_b32 s92, v254, 60
	v_lshlrev_b32_e32 v21, 2, v18
	v_lshlrev_b32_e32 v19, 2, v19
	v_readlane_b32 s93, v254, 61
	v_readlane_b32 s94, v254, 62
	v_readlane_b32 s95, v254, 63
	s_waitcnt vmcnt(31)
	v_add3_u32 v29, 0, v21, v19
	v_add3_u32 v21, 0, v19, v21
	v_add_u32_e32 v18, s11, v18
	v_add_u32_e32 v23, 0x2080, v22
	v_add_u32_e32 v24, 0x2088, v22
	v_add_u32_e32 v25, 0x4100, v22
	v_add_u32_e32 v26, 0x4108, v22
	v_add_u32_e32 v27, 0x6180, v22
	v_add_u32_e32 v28, 0x6188, v22
	s_waitcnt vmcnt(30)
	v_add_u32_e32 v30, 0x800, v21
	v_add_u32_e32 v31, 0x400, v29
	v_add_u32_e32 v32, 0x400, v21
	v_add_u32_e32 v33, 0xc00, v21
	v_ashrrev_i32_e32 v19, 31, v18
	v_readlane_b32 s80, v254, 44
	v_lshlrev_b64 v[18:19], 11, v[18:19]
	v_readlane_b32 s84, v254, 48
	v_readlane_b32 s85, v254, 49
	s_lshl_b32 s48, s10, 1
	v_lshlrev_b32_e32 v162, 1, v20
	v_lshl_add_u64 v[18:19], s[84:85], 0, v[18:19]
	v_lshl_add_u64 v[18:19], v[18:19], 0, s[48:49]
	v_readlane_b32 s96, v252, 0
	v_readlane_b32 s97, v252, 1
	v_lshl_add_u64 v[18:19], v[18:19], 0, v[162:163]
	v_readlane_b32 s98, v252, 2
	v_readlane_b32 s99, v252, 3
	s_mov_b64 s[24:25], s[96:97]
	v_readlane_b32 s81, v254, 45
	v_readlane_b32 s82, v254, 46
	v_readlane_b32 s83, v254, 47
	v_readlane_b32 s86, v254, 50
	v_readlane_b32 s87, v254, 51
	v_readlane_b32 s88, v254, 52
	v_readlane_b32 s89, v254, 53
	s_waitcnt vmcnt(3)
	ds_write2_b32 v22, v2, v3 offset1:1
	ds_write2_b32 v22, v4, v5 offset0:2 offset1:3
	s_waitcnt vmcnt(2)
	ds_write2_b32 v23, v6, v7 offset1:1
	ds_write2_b32 v24, v8, v9 offset1:1
	s_waitcnt vmcnt(1)
	ds_write2_b32 v25, v10, v11 offset1:1
	ds_write2_b32 v26, v12, v13 offset1:1
	s_waitcnt vmcnt(0)
	ds_write2_b32 v27, v14, v15 offset1:1
	ds_write2_b32 v28, v16, v17 offset1:1
	s_waitcnt lgkmcnt(0)
	s_barrier
	ds_read2_b32 v[2:3], v29 offset1:130
	ds_read2_b32 v[4:5], v21 offset0:65 offset1:195
	ds_read2_b32 v[6:7], v30 offset0:8 offset1:73
	ds_read2_b32 v[8:9], v30 offset0:138 offset1:203
	ds_read2_b32 v[10:11], v31 offset0:4 offset1:134
	ds_read2_b32 v[12:13], v32 offset0:69 offset1:199
	ds_read2_b32 v[14:15], v33 offset0:12 offset1:77
	ds_read2_b32 v[16:17], v33 offset0:142 offset1:207
	s_waitcnt lgkmcnt(6)
	v_cvt_pk_bf16_f32 v2, v2, v4
	v_cvt_pk_bf16_f32 v3, v3, v5
	s_waitcnt lgkmcnt(2)
	v_cvt_pk_bf16_f32 v4, v10, v12
	v_cvt_pk_bf16_f32 v5, v11, v13
	v_readlane_b32 s90, v254, 54
	v_readlane_b32 s91, v254, 55
	v_readlane_b32 s92, v254, 56
	v_readlane_b32 s93, v254, 57
	v_readlane_b32 s94, v254, 58
	v_readlane_b32 s95, v254, 59
	v_cvt_pk_bf16_f32 v6, v6, v7
	v_cvt_pk_bf16_f32 v7, v8, v9
	s_waitcnt lgkmcnt(1)
	v_cvt_pk_bf16_f32 v8, v14, v15
	s_waitcnt lgkmcnt(0)
	v_cvt_pk_bf16_f32 v9, v16, v17
	global_store_dwordx4 v[18:19], v[2:5], off
	global_store_dwordx4 v[18:19], v[6:9], off offset:16
	s_barrier
	s_mov_b64 s[6:7], -1
	s_cbranch_execz .LBB0_703
	s_branch .LBB0_707

.Lp0t_entry:
	v_readlane_b32 s80, v254, 38
	v_readlane_b32 s81, v254, 39
	v_readlane_b32 s82, v254, 48
	v_readlane_b32 s83, v254, 49
	s_nop 3
	s_mov_b32 s85, s21
	s_mov_b32 s86, s12
	s_cmpk_gt_i32 s86, 0x41f
	s_cbranch_scc1 .LBB0_726
	s_mov_b32 s84, s86
.Lp0t_klast:
	s_add_u32 s0, s84, s85
	s_cmpk_gt_u32 s0, 0x41f
	s_cbranch_scc1 .Lp0t_kdone
	s_mov_b32 s84, s0
	s_branch .Lp0t_klast
.Lp0t_kdone:
	v_lshrrev_b32_e32 v112, 4, v1
	v_and_b32_e32 v113, 15, v1
	v_lshlrev_b32_e32 v113, 4, v113
	v_mul_u32_u24_e32 v114, 0x104, v112
	v_add_u32_e32 v114, v114, v113
	v_lshrrev_b32_e32 v116, 3, v1
	v_and_b32_e32 v117, 7, v1
	v_mul_u32_u24_e32 v115, 0x1040, v117
	v_lshl_add_u32 v115, v116, 2, v115
	v_lshlrev_b32_e32 v117, 5, v117
	s_mul_i32 s48, s85, 0
	s_add_u32 s48, s48, s86
	s_min_u32 s48, s48, s84
	s_sub_u32 s0, s48, 0xe0
	s_mul_i32 s2, s0, 0x4ed
	s_lshr_b32 s2, s2, 17
	s_mul_i32 s3, s2, 0x68
	s_sub_u32 s3, s0, s3
	s_mul_i32 s4, s2, 0x340000
	s_lshl_b32 s0, s3, 8
	s_add_u32 s4, s4, s0
	s_add_u32 s6, s80, s4
	s_addc_u32 s7, s81, 0
	s_lshl_b32 s4, s3, 17
	s_lshl_b32 s0, s2, 8
	s_add_u32 s4, s4, s0
	s_add_u32 s8, s82, s4
	s_addc_u32 s9, s83, 0
	s_movk_i32 s10, 0x6800
	s_movk_i32 s11, 0x800
	v_mul_lo_u32 v123, v112, s10
	v_add_u32_e32 v118, v123, v113
	s_lshl_b32 vcc_lo, s10, 5
	v_add_u32_e32 v119, vcc_lo, v118
	v_add_u32_e32 v120, vcc_lo, v119
	v_add_u32_e32 v121, vcc_lo, v120
	global_load_dwordx4 v[40:43], v118, s[6:7]
	global_load_dwordx4 v[44:47], v119, s[6:7]
	global_load_dwordx4 v[48:51], v120, s[6:7]
	global_load_dwordx4 v[52:55], v121, s[6:7]
	s_mul_i32 s48, s85, 1
	s_add_u32 s48, s48, s86
	s_min_u32 s48, s48, s84
	s_sub_u32 s0, s48, 0xe0
	s_mul_i32 s2, s0, 0x4ed
	s_lshr_b32 s2, s2, 17
	s_mul_i32 s3, s2, 0x68
	s_sub_u32 s3, s0, s3
	s_mul_i32 s4, s2, 0x340000
	s_lshl_b32 s0, s3, 8
	s_add_u32 s4, s4, s0
	s_add_u32 s6, s80, s4
	s_addc_u32 s7, s81, 0
	s_lshl_b32 s4, s3, 17
	s_lshl_b32 s0, s2, 8
	s_add_u32 s4, s4, s0
	s_add_u32 s8, s82, s4
	s_addc_u32 s9, s83, 0
	s_movk_i32 s10, 0x6800
	s_movk_i32 s11, 0x800
	v_mul_lo_u32 v123, v112, s10
	v_add_u32_e32 v118, v123, v113
	s_lshl_b32 vcc_lo, s10, 5
	v_add_u32_e32 v119, vcc_lo, v118
	v_add_u32_e32 v120, vcc_lo, v119
	v_add_u32_e32 v121, vcc_lo, v120
	global_load_dwordx4 v[56:59], v118, s[6:7]
	global_load_dwordx4 v[60:63], v119, s[6:7]
	global_load_dwordx4 v[64:67], v120, s[6:7]
	global_load_dwordx4 v[68:71], v121, s[6:7]
	s_mul_i32 s48, s85, 2
	s_add_u32 s48, s48, s86
	s_min_u32 s48, s48, s84
	s_sub_u32 s0, s48, 0xe0
	s_mul_i32 s2, s0, 0x4ed
	s_lshr_b32 s2, s2, 17
	s_mul_i32 s3, s2, 0x68
	s_sub_u32 s3, s0, s3
	s_mul_i32 s4, s2, 0x340000
	s_lshl_b32 s0, s3, 8
	s_add_u32 s4, s4, s0
	s_add_u32 s6, s80, s4
	s_addc_u32 s7, s81, 0
	s_lshl_b32 s4, s3, 17
	s_lshl_b32 s0, s2, 8
	s_add_u32 s4, s4, s0
	s_add_u32 s8, s82, s4
	s_addc_u32 s9, s83, 0
	s_movk_i32 s10, 0x6800
	s_movk_i32 s11, 0x800
	v_mul_lo_u32 v123, v112, s10
	v_add_u32_e32 v118, v123, v113
	s_lshl_b32 vcc_lo, s10, 5
	v_add_u32_e32 v119, vcc_lo, v118
	v_add_u32_e32 v120, vcc_lo, v119
	v_add_u32_e32 v121, vcc_lo, v120
	global_load_dwordx4 v[72:75], v118, s[6:7]
	global_load_dwordx4 v[76:79], v119, s[6:7]
	global_load_dwordx4 v[80:83], v120, s[6:7]
	global_load_dwordx4 v[84:87], v121, s[6:7]
	s_waitcnt vmcnt(8)
	ds_write_b32 v114, v40 offset:0
	ds_write_b32 v114, v41 offset:4
	ds_write_b32 v114, v42 offset:8
	ds_write_b32 v114, v43 offset:12
	ds_write_b32 v114, v44 offset:8320
	ds_write_b32 v114, v45 offset:8324
	ds_write_b32 v114, v46 offset:8328
	ds_write_b32 v114, v47 offset:8332
	ds_write_b32 v114, v48 offset:16640
	ds_write_b32 v114, v49 offset:16644
	ds_write_b32 v114, v50 offset:16648
	ds_write_b32 v114, v51 offset:16652
	ds_write_b32 v114, v52 offset:24960
	ds_write_b32 v114, v53 offset:24964
	ds_write_b32 v114, v54 offset:24968
	ds_write_b32 v114, v55 offset:24972
	s_waitcnt lgkmcnt(0)
	s_barrier
	ds_read_b32 v88, v115 offset:0
	ds_read_b32 v89, v115 offset:260
	ds_read_b32 v90, v115 offset:520
	ds_read_b32 v91, v115 offset:780
	ds_read_b32 v92, v115 offset:1040
	ds_read_b32 v93, v115 offset:1300
	ds_read_b32 v94, v115 offset:1560
	ds_read_b32 v95, v115 offset:1820
	ds_read_b32 v96, v115 offset:2080
	ds_read_b32 v97, v115 offset:2340
	ds_read_b32 v98, v115 offset:2600
	ds_read_b32 v99, v115 offset:2860
	ds_read_b32 v100, v115 offset:3120
	ds_read_b32 v101, v115 offset:3380
	ds_read_b32 v102, v115 offset:3640
	ds_read_b32 v103, v115 offset:3900
	s_mul_i32 s48, s85, 0
	s_add_u32 s48, s48, s86
	s_min_u32 s48, s48, s84
	s_sub_u32 s0, s48, 0xe0
	s_mul_i32 s2, s0, 0x4ed
	s_lshr_b32 s2, s2, 17
	s_mul_i32 s3, s2, 0x68
	s_sub_u32 s3, s0, s3
	s_mul_i32 s4, s2, 0x340000
	s_lshl_b32 s0, s3, 8
	s_add_u32 s4, s4, s0
	s_add_u32 s6, s80, s4
	s_addc_u32 s7, s81, 0
	s_lshl_b32 s4, s3, 17
	s_lshl_b32 s0, s2, 8
	s_add_u32 s4, s4, s0
	s_add_u32 s8, s82, s4
	s_addc_u32 s9, s83, 0
	s_movk_i32 s10, 0x6800
	s_movk_i32 s11, 0x800
	v_mul_lo_u32 v122, v116, s11
	v_add_u32_e32 v122, v122, v117
	s_waitcnt lgkmcnt(0)
	v_cvt_pk_bf16_f32 v104, v88, v89
	v_cvt_pk_bf16_f32 v105, v90, v91
	v_cvt_pk_bf16_f32 v106, v92, v93
	v_cvt_pk_bf16_f32 v107, v94, v95
	v_cvt_pk_bf16_f32 v108, v96, v97
	v_cvt_pk_bf16_f32 v109, v98, v99
	v_cvt_pk_bf16_f32 v110, v100, v101
	v_cvt_pk_bf16_f32 v111, v102, v103
	global_store_dwordx4 v122, v[104:107], s[8:9]
	global_store_dwordx4 v122, v[108:111], s[8:9] offset:16
	s_nop 1
	s_mul_i32 s48, s85, 3
	s_add_u32 s48, s48, s86
	s_min_u32 s48, s48, s84
	s_sub_u32 s0, s48, 0xe0
	s_mul_i32 s2, s0, 0x4ed
	s_lshr_b32 s2, s2, 17
	s_mul_i32 s3, s2, 0x68
	s_sub_u32 s3, s0, s3
	s_mul_i32 s4, s2, 0x340000
	s_lshl_b32 s0, s3, 8
	s_add_u32 s4, s4, s0
	s_add_u32 s6, s80, s4
	s_addc_u32 s7, s81, 0
	s_lshl_b32 s4, s3, 17
	s_lshl_b32 s0, s2, 8
	s_add_u32 s4, s4, s0
	s_add_u32 s8, s82, s4
	s_addc_u32 s9, s83, 0
	s_movk_i32 s10, 0x6800
	s_movk_i32 s11, 0x800
	v_mul_lo_u32 v123, v112, s10
	v_add_u32_e32 v118, v123, v113
	s_lshl_b32 vcc_lo, s10, 5
	v_add_u32_e32 v119, vcc_lo, v118
	v_add_u32_e32 v120, vcc_lo, v119
	v_add_u32_e32 v121, vcc_lo, v120
	global_load_dwordx4 v[40:43], v118, s[6:7]
	global_load_dwordx4 v[44:47], v119, s[6:7]
	global_load_dwordx4 v[48:51], v120, s[6:7]
	global_load_dwordx4 v[52:55], v121, s[6:7]
	s_waitcnt vmcnt(10)
	ds_write_b32 v114, v56 offset:33792
	ds_write_b32 v114, v57 offset:33796
	ds_write_b32 v114, v58 offset:33800
	ds_write_b32 v114, v59 offset:33804
	ds_write_b32 v114, v60 offset:42112
	ds_write_b32 v114, v61 offset:42116
	ds_write_b32 v114, v62 offset:42120
	ds_write_b32 v114, v63 offset:42124
	ds_write_b32 v114, v64 offset:50432
	ds_write_b32 v114, v65 offset:50436
	ds_write_b32 v114, v66 offset:50440
	ds_write_b32 v114, v67 offset:50444
	ds_write_b32 v114, v68 offset:58752
	ds_write_b32 v114, v69 offset:58756
	ds_write_b32 v114, v70 offset:58760
	ds_write_b32 v114, v71 offset:58764
	s_waitcnt lgkmcnt(0)
	s_barrier
	ds_read_b32 v88, v115 offset:33792
	ds_read_b32 v89, v115 offset:34052
	ds_read_b32 v90, v115 offset:34312
	ds_read_b32 v91, v115 offset:34572
	ds_read_b32 v92, v115 offset:34832
	ds_read_b32 v93, v115 offset:35092
	ds_read_b32 v94, v115 offset:35352
	ds_read_b32 v95, v115 offset:35612
	ds_read_b32 v96, v115 offset:35872
	ds_read_b32 v97, v115 offset:36132
	ds_read_b32 v98, v115 offset:36392
	ds_read_b32 v99, v115 offset:36652
	ds_read_b32 v100, v115 offset:36912
	ds_read_b32 v101, v115 offset:37172
	ds_read_b32 v102, v115 offset:37432
	ds_read_b32 v103, v115 offset:37692
	s_mul_i32 s48, s85, 1
	s_add_u32 s48, s48, s86
	s_min_u32 s48, s48, s84
	s_sub_u32 s0, s48, 0xe0
	s_mul_i32 s2, s0, 0x4ed
	s_lshr_b32 s2, s2, 17
	s_mul_i32 s3, s2, 0x68
	s_sub_u32 s3, s0, s3
	s_mul_i32 s4, s2, 0x340000
	s_lshl_b32 s0, s3, 8
	s_add_u32 s4, s4, s0
	s_add_u32 s6, s80, s4
	s_addc_u32 s7, s81, 0
	s_lshl_b32 s4, s3, 17
	s_lshl_b32 s0, s2, 8
	s_add_u32 s4, s4, s0
	s_add_u32 s8, s82, s4
	s_addc_u32 s9, s83, 0
	s_movk_i32 s10, 0x6800
	s_movk_i32 s11, 0x800
	v_mul_lo_u32 v122, v116, s11
	v_add_u32_e32 v122, v122, v117
	s_waitcnt lgkmcnt(0)
	v_cvt_pk_bf16_f32 v104, v88, v89
	v_cvt_pk_bf16_f32 v105, v90, v91
	v_cvt_pk_bf16_f32 v106, v92, v93
	v_cvt_pk_bf16_f32 v107, v94, v95
	v_cvt_pk_bf16_f32 v108, v96, v97
	v_cvt_pk_bf16_f32 v109, v98, v99
	v_cvt_pk_bf16_f32 v110, v100, v101
	v_cvt_pk_bf16_f32 v111, v102, v103
	global_store_dwordx4 v122, v[104:107], s[8:9]
	global_store_dwordx4 v122, v[108:111], s[8:9] offset:16
	s_nop 1
	s_waitcnt vmcnt(8)
	ds_write_b32 v114, v72 offset:0
	ds_write_b32 v114, v73 offset:4
	ds_write_b32 v114, v74 offset:8
	ds_write_b32 v114, v75 offset:12
	ds_write_b32 v114, v76 offset:8320
	ds_write_b32 v114, v77 offset:8324
	ds_write_b32 v114, v78 offset:8328
	ds_write_b32 v114, v79 offset:8332
	ds_write_b32 v114, v80 offset:16640
	ds_write_b32 v114, v81 offset:16644
	ds_write_b32 v114, v82 offset:16648
	ds_write_b32 v114, v83 offset:16652
	ds_write_b32 v114, v84 offset:24960
	ds_write_b32 v114, v85 offset:24964
	ds_write_b32 v114, v86 offset:24968
	ds_write_b32 v114, v87 offset:24972
	s_waitcnt lgkmcnt(0)
	s_barrier
	ds_read_b32 v88, v115 offset:0
	ds_read_b32 v89, v115 offset:260
	ds_read_b32 v90, v115 offset:520
	ds_read_b32 v91, v115 offset:780
	ds_read_b32 v92, v115 offset:1040
	ds_read_b32 v93, v115 offset:1300
	ds_read_b32 v94, v115 offset:1560
	ds_read_b32 v95, v115 offset:1820
	ds_read_b32 v96, v115 offset:2080
	ds_read_b32 v97, v115 offset:2340
	ds_read_b32 v98, v115 offset:2600
	ds_read_b32 v99, v115 offset:2860
	ds_read_b32 v100, v115 offset:3120
	ds_read_b32 v101, v115 offset:3380
	ds_read_b32 v102, v115 offset:3640
	ds_read_b32 v103, v115 offset:3900
	s_mul_i32 s48, s85, 2
	s_add_u32 s48, s48, s86
	s_min_u32 s48, s48, s84
	s_sub_u32 s0, s48, 0xe0
	s_mul_i32 s2, s0, 0x4ed
	s_lshr_b32 s2, s2, 17
	s_mul_i32 s3, s2, 0x68
	s_sub_u32 s3, s0, s3
	s_mul_i32 s4, s2, 0x340000
	s_lshl_b32 s0, s3, 8
	s_add_u32 s4, s4, s0
	s_add_u32 s6, s80, s4
	s_addc_u32 s7, s81, 0
	s_lshl_b32 s4, s3, 17
	s_lshl_b32 s0, s2, 8
	s_add_u32 s4, s4, s0
	s_add_u32 s8, s82, s4
	s_addc_u32 s9, s83, 0
	s_movk_i32 s10, 0x6800
	s_movk_i32 s11, 0x800
	v_mul_lo_u32 v122, v116, s11
	v_add_u32_e32 v122, v122, v117
	s_waitcnt lgkmcnt(0)
	v_cvt_pk_bf16_f32 v104, v88, v89
	v_cvt_pk_bf16_f32 v105, v90, v91
	v_cvt_pk_bf16_f32 v106, v92, v93
	v_cvt_pk_bf16_f32 v107, v94, v95
	v_cvt_pk_bf16_f32 v108, v96, v97
	v_cvt_pk_bf16_f32 v109, v98, v99
	v_cvt_pk_bf16_f32 v110, v100, v101
	v_cvt_pk_bf16_f32 v111, v102, v103
	global_store_dwordx4 v122, v[104:107], s[8:9]
	global_store_dwordx4 v122, v[108:111], s[8:9] offset:16
	s_nop 1
	s_waitcnt vmcnt(4)
	ds_write_b32 v114, v40 offset:33792
	ds_write_b32 v114, v41 offset:33796
	ds_write_b32 v114, v42 offset:33800
	ds_write_b32 v114, v43 offset:33804
	ds_write_b32 v114, v44 offset:42112
	ds_write_b32 v114, v45 offset:42116
	ds_write_b32 v114, v46 offset:42120
	ds_write_b32 v114, v47 offset:42124
	ds_write_b32 v114, v48 offset:50432
	ds_write_b32 v114, v49 offset:50436
	ds_write_b32 v114, v50 offset:50440
	ds_write_b32 v114, v51 offset:50444
	ds_write_b32 v114, v52 offset:58752
	ds_write_b32 v114, v53 offset:58756
	ds_write_b32 v114, v54 offset:58760
	ds_write_b32 v114, v55 offset:58764
	s_waitcnt lgkmcnt(0)
	s_barrier
	ds_read_b32 v88, v115 offset:33792
	ds_read_b32 v89, v115 offset:34052
	ds_read_b32 v90, v115 offset:34312
	ds_read_b32 v91, v115 offset:34572
	ds_read_b32 v92, v115 offset:34832
	ds_read_b32 v93, v115 offset:35092
	ds_read_b32 v94, v115 offset:35352
	ds_read_b32 v95, v115 offset:35612
	ds_read_b32 v96, v115 offset:35872
	ds_read_b32 v97, v115 offset:36132
	ds_read_b32 v98, v115 offset:36392
	ds_read_b32 v99, v115 offset:36652
	ds_read_b32 v100, v115 offset:36912
	ds_read_b32 v101, v115 offset:37172
	ds_read_b32 v102, v115 offset:37432
	ds_read_b32 v103, v115 offset:37692
	s_mul_i32 s48, s85, 3
	s_add_u32 s48, s48, s86
	s_min_u32 s48, s48, s84
	s_sub_u32 s0, s48, 0xe0
	s_mul_i32 s2, s0, 0x4ed
	s_lshr_b32 s2, s2, 17
	s_mul_i32 s3, s2, 0x68
	s_sub_u32 s3, s0, s3
	s_mul_i32 s4, s2, 0x340000
	s_lshl_b32 s0, s3, 8
	s_add_u32 s4, s4, s0
	s_add_u32 s6, s80, s4
	s_addc_u32 s7, s81, 0
	s_lshl_b32 s4, s3, 17
	s_lshl_b32 s0, s2, 8
	s_add_u32 s4, s4, s0
	s_add_u32 s8, s82, s4
	s_addc_u32 s9, s83, 0
	s_movk_i32 s10, 0x6800
	s_movk_i32 s11, 0x800
	v_mul_lo_u32 v122, v116, s11
	v_add_u32_e32 v122, v122, v117
	s_waitcnt lgkmcnt(0)
	v_cvt_pk_bf16_f32 v104, v88, v89
	v_cvt_pk_bf16_f32 v105, v90, v91
	v_cvt_pk_bf16_f32 v106, v92, v93
	v_cvt_pk_bf16_f32 v107, v94, v95
	v_cvt_pk_bf16_f32 v108, v96, v97
	v_cvt_pk_bf16_f32 v109, v98, v99
	v_cvt_pk_bf16_f32 v110, v100, v101
	v_cvt_pk_bf16_f32 v111, v102, v103
	global_store_dwordx4 v122, v[104:107], s[8:9]
	global_store_dwordx4 v122, v[108:111], s[8:9] offset:16
	s_nop 1
	s_waitcnt vmcnt(0)
	s_barrier
	s_branch .LBB0_726

.LBB0_727:
	s_mov_b64 s[2:3], s[46:47]
	s_add_i32 s18, s2, 1
	s_cmp_ge_i32 s18, s3
	v_readlane_b32 s30, v254, 6
	v_readlane_b32 s38, v254, 8
	v_readlane_b32 s56, v254, 22
	v_readlane_b32 s31, v254, 7
	v_readlane_b32 s39, v254, 9
	v_readlane_b32 s57, v254, 23
	s_cbranch_scc1 .LBB0_781
	s_waitcnt vmcnt(0)
	s_waitcnt lgkmcnt(0)
	s_barrier
	s_mov_b64 s[2:3], exec
	v_readlane_b32 s4, v253, 7
	v_readlane_b32 s5, v253, 8
	s_and_b64 s[4:5], s[2:3], s[4:5]
	s_mov_b64 exec, s[4:5]
	s_cbranch_execz .LBB0_780
	s_add_i32 s13, 0, 0x24000
	s_mov_b64 s[4:5], src_shared_base
	s_cmp_lg_u32 s13, -1
	s_cselect_b32 s4, s13, 0
	s_cselect_b32 s6, s5, 0
	s_add_i32 s12, 0, 0x24004
	s_cmp_lg_u32 s12, -1
	v_mov_b32_e32 v2, s4
	v_mov_b32_e32 v3, s6
	s_cselect_b32 s4, s12, 0
	s_cselect_b32 s5, s5, 0
	s_waitcnt vmcnt(0) expcnt(0) lgkmcnt(0)
	s_and_b32 s4, s101, 0xffff
	v_mov_b32_e32 v4, s4
	v_mov_b32_e32 v2, s4
	v_mov_b32_e32 v3, s5
	s_lshr_b32 s4, s101, 16
	v_mov_b32_e32 v2, s4
	s_waitcnt vmcnt(0) lgkmcnt(0)
	v_cmp_eq_u32_e32 vcc, 0, v4
	s_and_saveexec_b64 s[4:5], vcc
	s_cbranch_execz .LBB0_744
	s_mov_b32 s14, 1
	s_branch .LBB0_732

.LBB0_743:
	v_readlane_b32 s6, v253, 40
	v_readlane_b32 s7, v253, 41
	v_cmp_ne_u32_e32 vcc, 0, v12
	s_cmp_lg_u32 s13, -1
	v_cndmask_b32_e64 v18, 0, v12, s[6:7]
	v_readlane_b32 s6, v253, 38
	v_readlane_b32 s7, v253, 39
	v_cndmask_b32_e64 v12, 0, 1, vcc
	v_cmp_ne_u32_e32 vcc, 0, v2
	v_cndmask_b32_e64 v18, v18, v2, s[6:7]
	v_readlane_b32 s6, v253, 36
	v_readlane_b32 s7, v253, 37
	v_addc_co_u32_e32 v2, vcc, 0, v12, vcc
	s_nop 0
	v_cndmask_b32_e64 v18, v18, v3, s[6:7]
	v_readlane_b32 s6, v253, 34
	v_readlane_b32 s7, v253, 35
	v_cmp_ne_u32_e32 vcc, 0, v3
	s_cselect_b32 s8, s13, 0
	v_cndmask_b32_e64 v18, v18, v4, s[6:7]
	v_readlane_b32 s6, v253, 32
	v_readlane_b32 s7, v253, 33
	v_cndmask_b32_e64 v3, 0, 1, vcc
	v_cmp_ne_u32_e32 vcc, 0, v4
	v_cndmask_b32_e64 v18, v18, v5, s[6:7]
	v_readlane_b32 s6, v253, 30
	v_readlane_b32 s7, v253, 31
	v_addc_co_u32_e32 v2, vcc, v2, v3, vcc
	s_nop 0
	v_cndmask_b32_e64 v18, v18, v6, s[6:7]
	v_readlane_b32 s6, v253, 28
	v_readlane_b32 s7, v253, 29
	v_cmp_ne_u32_e32 vcc, 0, v5
	s_nop 0
	v_cndmask_b32_e64 v18, v18, v7, s[6:7]
	v_readlane_b32 s6, v253, 26
	v_readlane_b32 s7, v253, 27
	v_cndmask_b32_e64 v3, 0, 1, vcc
	v_cmp_ne_u32_e32 vcc, 0, v6
	v_cndmask_b32_e64 v18, v18, v8, s[6:7]
	v_readlane_b32 s6, v253, 24
	v_readlane_b32 s7, v253, 25
	v_addc_co_u32_e32 v2, vcc, v2, v3, vcc
	s_nop 0
	v_cndmask_b32_e64 v18, v18, v9, s[6:7]
	v_readlane_b32 s6, v253, 22
	v_readlane_b32 s7, v253, 23
	v_cmp_ne_u32_e32 vcc, 0, v7
	v_mov_b32_e32 v6, s8
	v_cndmask_b32_e64 v18, v18, v10, s[6:7]
	v_readlane_b32 s6, v253, 20
	v_readlane_b32 s7, v253, 21
	v_cndmask_b32_e64 v3, 0, 1, vcc
	v_cmp_ne_u32_e32 vcc, 0, v8
	v_cndmask_b32_e64 v18, v18, v11, s[6:7]
	v_readlane_b32 s6, v253, 18
	v_addc_co_u32_e32 v2, vcc, v2, v3, vcc
	v_readlane_b32 s7, v253, 19
	v_cmp_ne_u32_e32 vcc, 0, v9
	s_nop 0
	v_cndmask_b32_e64 v18, v18, v13, s[6:7]
	v_readlane_b32 s6, v253, 16
	v_cndmask_b32_e64 v3, 0, 1, vcc
	v_cmp_ne_u32_e32 vcc, 0, v10
	v_readlane_b32 s7, v253, 17
	s_nop 0
	v_addc_co_u32_e32 v2, vcc, v2, v3, vcc
	v_cndmask_b32_e64 v18, v18, v14, s[6:7]
	v_readlane_b32 s6, v253, 14
	v_cmp_ne_u32_e32 vcc, 0, v11
	v_readlane_b32 s7, v253, 15
	s_nop 0
	v_cndmask_b32_e64 v3, 0, 1, vcc
	v_cmp_ne_u32_e32 vcc, 0, v13
	v_cndmask_b32_e64 v18, v18, v15, s[6:7]
	v_readlane_b32 s6, v253, 12
	v_addc_co_u32_e32 v2, vcc, v2, v3, vcc
	v_readlane_b32 s7, v253, 13
	v_cmp_ne_u32_e32 vcc, 0, v14
	s_nop 0
	v_cndmask_b32_e64 v18, v18, v16, s[6:7]
	v_readlane_b32 s6, v253, 10
	v_cndmask_b32_e64 v3, 0, 1, vcc
	v_cmp_ne_u32_e32 vcc, 0, v15
	v_readlane_b32 s7, v253, 11
	s_nop 0
	v_addc_co_u32_e32 v2, vcc, v2, v3, vcc
	v_cndmask_b32_e64 v18, v18, v17, s[6:7]
	v_cmp_ne_u32_e32 vcc, 0, v16
	s_mov_b64 s[6:7], src_shared_base
	s_cselect_b32 s6, s7, 0
	v_cndmask_b32_e64 v3, 0, 1, vcc
	v_cmp_ne_u32_e32 vcc, 0, v17
	s_cmp_lg_u32 s12, -1
	v_max_u32_e32 v4, 1, v18
	v_addc_co_u32_e32 v2, vcc, v2, v3, vcc
	v_mov_b32_e32 v7, s6
	s_cselect_b32 s6, s12, 0
	s_cselect_b32 s7, s7, 0
	v_max_u32_e32 v2, 1, v2
	flat_store_dword v[6:7], v4 sc0 sc1
	s_waitcnt vmcnt(0)
	v_mov_b32_e32 v6, s6
	v_mov_b32_e32 v7, s7
	flat_store_dword v[6:7], v2 sc0 sc1
	s_waitcnt vmcnt(0)
	v_readfirstlane_b32 s8, v4
	v_readfirstlane_b32 s101, v2
	s_lshl_b32 s101, s101, 16
	s_or_b32 s101, s101, s8

.LBB0_763:
	s_or_b64 exec, exec, s[6:7]
	s_waitcnt vmcnt(0)
	v_readfirstlane_b32 s4, v4
	v_cvt_f32_u32_e32 v4, v2
	v_sub_u32_e32 v5, 0, v2
	v_add_u32_e32 v3, s4, v3
	s_mov_b64 s[6:7], 0
	v_rcp_iflag_f32_e32 v4, v4
	s_nop 0
	v_mul_f32_e32 v4, 0x4f7ffffe, v4
	v_cvt_u32_f32_e32 v4, v4
	v_mul_lo_u32 v5, v5, v4
	v_mul_hi_u32 v5, v4, v5
	v_add_u32_e32 v4, v4, v5
	v_mul_hi_u32 v4, v3, v4
	v_mul_lo_u32 v5, v4, v2
	v_sub_u32_e32 v5, v3, v5
	v_cmp_ge_u32_e32 vcc, v5, v2
	v_add_u32_e32 v6, 1, v4
	s_nop 0
	v_cndmask_b32_e32 v4, v4, v6, vcc
	v_sub_u32_e32 v6, v5, v2
	v_cndmask_b32_e32 v5, v5, v6, vcc
	v_cmp_ge_u32_e32 vcc, v5, v2
	v_add_u32_e32 v5, 1, v4
	s_nop 0
	v_cndmask_b32_e32 v4, v4, v5, vcc
	v_add_u32_e32 v5, 1, v3
	v_mad_u64_u32 v[2:3], s[4:5], v2, v4, v[2:3]
	s_nop 0
	v_mov_b32_e32 v6, v2
	v_readlane_b32 s4, v253, 48
	v_readlane_b32 s5, v253, 49
	v_cmp_ne_u32_e32 vcc, v5, v2
	s_nop 0
	v_mov_b64_e32 v[2:3], s[4:5]
	s_and_saveexec_b64 s[4:5], vcc
	s_cbranch_execz .LBB0_775
	v_readlane_b32 s6, v253, 46
	v_readlane_b32 s7, v253, 47
	s_mov_b64 s[8:9], 0
	s_nop 3
	global_load_dword v2, v163, s[6:7] sc1
	s_waitcnt vmcnt(0)
	v_cmp_lt_u32_e32 vcc, v2, v6
	s_and_saveexec_b64 s[6:7], vcc
	s_cbranch_execz .LBB0_774
	s_mov_b32 s19, 1
	s_branch .LBB0_767

.LBB0_769:
	v_readlane_b32 s12, v253, 46
	v_readlane_b32 s13, v253, 47
	s_add_i32 s19, s19, 1
	s_mov_b64 s[14:15], -1
	s_nop 2
	global_load_dword v2, v163, s[12:13] sc1
	s_waitcnt vmcnt(0)
	v_cmp_ge_u32_e32 vcc, v2, v6
	s_orn2_b64 s[12:13], vcc, exec
	s_branch .LBB0_766

	.amdhsa_kernel _Z11mega_kernel6Paramsii
		.amdhsa_group_segment_fixed_size 0
		.amdhsa_private_segment_fixed_size 0
		.amdhsa_kernarg_size 568
		.amdhsa_user_sgpr_count 2
		.amdhsa_user_sgpr_dispatch_ptr 0
		.amdhsa_user_sgpr_queue_ptr 0
		.amdhsa_user_sgpr_kernarg_segment_ptr 1
		.amdhsa_user_sgpr_dispatch_id 0
		.amdhsa_user_sgpr_kernarg_preload_length 0
		.amdhsa_user_sgpr_kernarg_preload_offset 0
		.amdhsa_user_sgpr_private_segment_size 0
		.amdhsa_uses_dynamic_stack 0
		.amdhsa_enable_private_segment 0
		.amdhsa_system_sgpr_workgroup_id_x 1
		.amdhsa_system_sgpr_workgroup_id_y 0
		.amdhsa_system_sgpr_workgroup_id_z 0
		.amdhsa_system_sgpr_workgroup_info 0
		.amdhsa_system_vgpr_workitem_id 2
		.amdhsa_next_free_vgpr 255
		.amdhsa_next_free_sgpr 102
		.amdhsa_accum_offset 256
		.amdhsa_reserve_vcc 1
		.amdhsa_float_round_mode_32 0
		.amdhsa_float_round_mode_16_64 0
		.amdhsa_float_denorm_mode_32 3
		.amdhsa_float_denorm_mode_16_64 3
		.amdhsa_dx10_clamp 1
		.amdhsa_ieee_mode 1
		.amdhsa_fp16_overflow 0
		.amdhsa_tg_split 0
		.amdhsa_exception_fp_ieee_invalid_op 0
		.amdhsa_exception_fp_denorm_src 0
		.amdhsa_exception_fp_ieee_div_zero 0
		.amdhsa_exception_fp_ieee_overflow 0
		.amdhsa_exception_fp_ieee_underflow 0
		.amdhsa_exception_fp_ieee_inexact 0
		.amdhsa_exception_int_div_zero 0
	.end_amdhsa_kernel

amdhsa.kernels:
  - .agpr_count:     0
    .args:
      - .offset:         0
        .size:           304
        .value_kind:     by_value
      - .offset:         304
        .size:           4
        .value_kind:     by_value
      - .offset:         308
        .size:           4
        .value_kind:     by_value
      - .offset:         312
        .size:           4
        .value_kind:     hidden_block_count_x
      - .offset:         316
        .size:           4
        .value_kind:     hidden_block_count_y
      - .offset:         320
        .size:           4
        .value_kind:     hidden_block_count_z
      - .offset:         324
        .size:           2
        .value_kind:     hidden_group_size_x
      - .offset:         326
        .size:           2
        .value_kind:     hidden_group_size_y
      - .offset:         328
        .size:           2
        .value_kind:     hidden_group_size_z
      - .offset:         330
        .size:           2
        .value_kind:     hidden_remainder_x
      - .offset:         332
        .size:           2
        .value_kind:     hidden_remainder_y
      - .offset:         334
        .size:           2
        .value_kind:     hidden_remainder_z
      - .offset:         352
        .size:           8
        .value_kind:     hidden_global_offset_x
      - .offset:         360
        .size:           8
        .value_kind:     hidden_global_offset_y
      - .offset:         368
        .size:           8
        .value_kind:     hidden_global_offset_z
      - .offset:         376
        .size:           2
        .value_kind:     hidden_grid_dims
      - .offset:         400
        .size:           8
        .value_kind:     hidden_multigrid_sync_arg
      - .offset:         432
        .size:           4
        .value_kind:     hidden_dynamic_lds_size
    .group_segment_fixed_size: 0
    .kernarg_segment_align: 8
    .kernarg_segment_size: 568
    .language:       OpenCL C
    .language_version:
      - 2
      - 0
    .max_flat_workgroup_size: 512
    .name:           _Z11mega_kernel6Paramsii
    .private_segment_fixed_size: 0
    .sgpr_count:     108
    .sgpr_spill_count: 193
    .symbol:         _Z11mega_kernel6Paramsii.kd
    .uniform_work_group_size: 1
    .uses_dynamic_stack: false
    .vgpr_count:     255
    .vgpr_spill_count: 0
    .wavefront_size: 64
